# gemm8 epilogue stores write-through (sc1) so the grid-barrier L2 writeback is cheaper
# speedup vs baseline: 1.0355x; 1.0047x over previous
.LBB0_195:
	ds_read_b128 v[160:163], v196
	ds_read_b128 v[164:167], v198
	ds_read_b128 v[180:183], v198 offset:64
	ds_read_b128 v[168:171], v196 offset:64
	ds_read_b128 v[172:175], v198 offset:2304
	ds_read_b128 v[206:209], v198 offset:2368
	ds_read_b128 v[176:179], v198 offset:4608
	ds_read_b128 v[210:213], v198 offset:4672
	ds_read_b128 v[184:187], v198 offset:6912
	ds_read_b128 v[214:217], v198 offset:6976
	s_waitcnt lgkmcnt(8)
	v_mfma_f32_16x16x32_bf16 v[156:159], v[164:167], v[160:163], v[156:159]
	s_add_i32 s49, s49, 2
	s_add_u32 s50, s45, 0xffffff80
	s_addc_u32 s51, s48, -1
	s_waitcnt lgkmcnt(5)
	v_mfma_f32_16x16x32_bf16 v[152:155], v[172:175], v[160:163], v[152:155]
	s_add_u32 s56, s30, 0xffffff80
	s_addc_u32 s57, s31, -1
	s_cmp_gt_u32 s49, 13
	s_waitcnt lgkmcnt(3)
	v_mfma_f32_16x16x32_bf16 v[148:151], v[176:179], v[160:163], v[148:151]
	s_cselect_b64 s[4:5], -1, 0
	s_and_b64 vcc, s[4:5], exec
	s_cselect_b32 s5, s11, s51
	s_waitcnt lgkmcnt(1)
	v_mfma_f32_16x16x32_bf16 v[144:147], v[184:187], v[160:163], v[144:147]
	ds_read_b128 v[160:163], v196 offset:2304
	ds_read_b128 v[188:191], v196 offset:2368
	s_cselect_b32 s4, s10, s50
	s_cselect_b32 s51, s13, s57
	s_waitcnt lgkmcnt(1)
	v_mfma_f32_16x16x32_bf16 v[140:143], v[164:167], v[160:163], v[140:143]
	s_cselect_b32 s50, s12, s56
	s_cmp_gt_u32 s49, 12
	v_mfma_f32_16x16x32_bf16 v[136:139], v[172:175], v[160:163], v[136:139]
	v_mfma_f32_16x16x32_bf16 v[132:135], v[176:179], v[160:163], v[132:135]
	v_mfma_f32_16x16x32_bf16 v[128:131], v[184:187], v[160:163], v[128:131]
	ds_read_b128 v[160:163], v196 offset:4608
	ds_read_b128 v[218:221], v196 offset:4672
	s_waitcnt lgkmcnt(1)
	v_mfma_f32_16x16x32_bf16 v[124:127], v[164:167], v[160:163], v[124:127]
	v_mfma_f32_16x16x32_bf16 v[120:123], v[172:175], v[160:163], v[120:123]
	v_mfma_f32_16x16x32_bf16 v[116:119], v[176:179], v[160:163], v[116:119]
	v_mfma_f32_16x16x32_bf16 v[112:115], v[184:187], v[160:163], v[112:115]
	ds_read_b128 v[160:163], v196 offset:6912
	ds_read_b128 v[222:225], v196 offset:6976
	s_waitcnt lgkmcnt(1)
	v_mfma_f32_16x16x32_bf16 v[108:111], v[164:167], v[160:163], v[108:111]
	v_mfma_f32_16x16x32_bf16 v[104:107], v[172:175], v[160:163], v[104:107]
	v_mfma_f32_16x16x32_bf16 v[100:103], v[176:179], v[160:163], v[100:103]
	v_mfma_f32_16x16x32_bf16 v[96:99], v[184:187], v[160:163], v[96:99]
	ds_read_b128 v[160:163], v196 offset:9216
	ds_read_b128 v[226:229], v196 offset:9280
	s_waitcnt lgkmcnt(1)
	v_mfma_f32_16x16x32_bf16 v[92:95], v[164:167], v[160:163], v[92:95]
	v_mfma_f32_16x16x32_bf16 v[88:91], v[172:175], v[160:163], v[88:91]
	v_mfma_f32_16x16x32_bf16 v[84:87], v[176:179], v[160:163], v[84:87]
	v_mfma_f32_16x16x32_bf16 v[80:83], v[184:187], v[160:163], v[80:83]
	ds_read_b128 v[160:163], v196 offset:11520
	ds_read_b128 v[230:233], v196 offset:11584
	s_waitcnt lgkmcnt(1)
	v_mfma_f32_16x16x32_bf16 v[68:71], v[164:167], v[160:163], v[68:71]
	v_mfma_f32_16x16x32_bf16 v[64:67], v[172:175], v[160:163], v[64:67]
	v_mfma_f32_16x16x32_bf16 v[60:63], v[176:179], v[160:163], v[60:63]
	v_mfma_f32_16x16x32_bf16 v[56:59], v[184:187], v[160:163], v[56:59]
	ds_read_b128 v[160:163], v196 offset:13824
	ds_read_b128 v[234:237], v196 offset:13888
	s_waitcnt lgkmcnt(1)
	v_mfma_f32_16x16x32_bf16 v[52:55], v[164:167], v[160:163], v[52:55]
	v_mfma_f32_16x16x32_bf16 v[48:51], v[172:175], v[160:163], v[48:51]
	v_mfma_f32_16x16x32_bf16 v[44:47], v[176:179], v[160:163], v[44:47]
	v_mfma_f32_16x16x32_bf16 v[40:43], v[184:187], v[160:163], v[40:43]
	ds_read_b128 v[160:163], v196 offset:16128
	ds_read_b128 v[238:241], v196 offset:16192
	s_waitcnt vmcnt(6)
	ds_write_b128 v194, v[4:7] offset:36864
	s_waitcnt vmcnt(5)
	ds_write_b128 v194, v[8:11] offset:46080
	s_waitcnt vmcnt(4)
	ds_write_b128 v194, v[12:15] offset:55296
	s_waitcnt vmcnt(3)
	ds_write_b128 v194, v[16:19] offset:64512
	s_waitcnt vmcnt(3)
	ds_write_b128 v199, v[0:3]
	s_waitcnt vmcnt(2)
	ds_write_b128 v199, v[20:23] offset:9216
	v_mfma_f32_16x16x32_bf16 v[20:23], v[214:217], v[226:229], v[80:83]
	s_waitcnt vmcnt(1)
	ds_write_b128 v199, v[24:27] offset:18432
	s_waitcnt vmcnt(0)
	ds_write_b128 v199, v[28:31] offset:27648
	v_lshl_add_u64 v[80:81], s[4:5], 0, v[192:193]
	v_mfma_f32_16x16x32_bf16 v[24:27], v[180:183], v[230:233], v[68:71]
	v_lshl_add_u64 v[82:83], s[50:51], 0, v[192:193]
	s_cselect_b32 s51, s44, s31
	s_cselect_b32 s50, s43, s30
	v_add_co_u32_e64 v68, s[4:5], s14, v80
	v_mfma_f32_16x16x32_bf16 v[28:31], v[206:209], v[230:233], v[64:67]
	s_nop 0
	v_addc_co_u32_e64 v69, s[4:5], 0, v81, s[4:5]
	s_nop 0
	v_add_co_u32_e64 v64, s[4:5], s15, v80
	s_waitcnt lgkmcnt(9)
	v_mfma_f32_16x16x32_bf16 v[36:39], v[164:167], v[160:163], v[36:39]
	v_addc_co_u32_e64 v65, s[4:5], 0, v81, s[4:5]
	v_add_co_u32_e64 v66, s[4:5], s27, v80
	v_mfma_f32_16x16x32_bf16 v[32:35], v[172:175], v[160:163], v[32:35]
	s_nop 0
	v_addc_co_u32_e64 v67, s[4:5], 0, v81, s[4:5]
	v_add_co_u32_e64 v70, s[4:5], s14, v82
	v_mfma_f32_16x16x32_bf16 v[76:79], v[176:179], v[160:163], v[76:79]
	s_nop 0
	v_addc_co_u32_e64 v71, s[4:5], 0, v83, s[4:5]
	global_load_dwordx4 v[164:167], v[82:83], off
	v_mfma_f32_16x16x32_bf16 v[72:75], v[184:187], v[160:163], v[72:75]
	global_load_dwordx4 v[160:163], v[80:81], off
	v_add_co_u32_e64 v80, s[4:5], s15, v82
	v_mfma_f32_16x16x32_bf16 v[156:159], v[180:183], v[168:171], v[156:159]
	s_nop 0
	v_addc_co_u32_e64 v81, s[4:5], 0, v83, s[4:5]
	v_add_co_u32_e64 v82, s[4:5], s27, v82
	v_mfma_f32_16x16x32_bf16 v[152:155], v[206:209], v[168:171], v[152:155]
	s_nop 0
	v_addc_co_u32_e64 v83, s[4:5], 0, v83, s[4:5]
	s_cselect_b32 s5, s25, s48
	v_mfma_f32_16x16x32_bf16 v[148:151], v[210:213], v[168:171], v[148:151]
	s_cselect_b32 s4, s23, s45
	s_add_u32 s30, s30, 0x100
	s_addc_u32 s31, s31, 0
	v_mfma_f32_16x16x32_bf16 v[144:147], v[214:217], v[168:171], v[144:147]
	global_load_dwordx4 v[168:171], v[68:69], off
	global_load_dwordx4 v[172:175], v[64:65], off
	global_load_dwordx4 v[176:179], v[66:67], off
	s_add_u32 s45, s45, 0x100
	s_addc_u32 s48, s48, 0
	v_mfma_f32_16x16x32_bf16 v[140:143], v[180:183], v[188:191], v[140:143]
	v_mfma_f32_16x16x32_bf16 v[136:139], v[206:209], v[188:191], v[136:139]
	v_mfma_f32_16x16x32_bf16 v[132:135], v[210:213], v[188:191], v[132:135]
	v_mfma_f32_16x16x32_bf16 v[128:131], v[214:217], v[188:191], v[128:131]
	v_mfma_f32_16x16x32_bf16 v[124:127], v[180:183], v[218:221], v[124:127]
	v_mfma_f32_16x16x32_bf16 v[108:111], v[180:183], v[222:225], v[108:111]
	v_mfma_f32_16x16x32_bf16 v[8:11], v[180:183], v[226:229], v[92:95]
	v_mfma_f32_16x16x32_bf16 v[52:55], v[180:183], v[234:237], v[52:55]
	s_waitcnt lgkmcnt(8)
	v_mfma_f32_16x16x32_bf16 v[36:39], v[180:183], v[238:241], v[36:39]
	global_load_dwordx4 v[180:183], v[70:71], off
	global_load_dwordx4 v[184:187], v[80:81], off
	global_load_dwordx4 v[188:191], v[82:83], off
	s_waitcnt lgkmcnt(0)
	s_barrier
	ds_read_b128 v[68:71], v196 offset:36864
	v_mfma_f32_16x16x32_bf16 v[120:123], v[206:209], v[218:221], v[120:123]
	v_mfma_f32_16x16x32_bf16 v[116:119], v[210:213], v[218:221], v[116:119]
	v_mfma_f32_16x16x32_bf16 v[104:107], v[206:209], v[222:225], v[104:107]
	v_mfma_f32_16x16x32_bf16 v[4:7], v[210:213], v[222:225], v[100:103]
	v_mfma_f32_16x16x32_bf16 v[0:3], v[214:217], v[222:225], v[96:99]
	v_mfma_f32_16x16x32_bf16 v[12:15], v[206:209], v[226:229], v[88:91]
	v_mfma_f32_16x16x32_bf16 v[16:19], v[210:213], v[226:229], v[84:87]
	v_mfma_f32_16x16x32_bf16 v[60:63], v[210:213], v[230:233], v[60:63]
	v_mfma_f32_16x16x32_bf16 v[48:51], v[206:209], v[234:237], v[48:51]
	v_mfma_f32_16x16x32_bf16 v[44:47], v[210:213], v[234:237], v[44:47]
	v_mfma_f32_16x16x32_bf16 v[32:35], v[206:209], v[238:241], v[32:35]
	ds_read_b128 v[84:87], v200
	ds_read_b128 v[206:209], v200 offset:64
	ds_read_b128 v[88:91], v196 offset:36928
	v_mfma_f32_16x16x32_bf16 v[64:67], v[210:213], v[238:241], v[76:79]
	ds_read_b128 v[96:99], v200 offset:2304
	ds_read_b128 v[210:213], v200 offset:2368
	v_mfma_f32_16x16x32_bf16 v[80:83], v[214:217], v[238:241], v[72:75]
	s_waitcnt lgkmcnt(4)
	v_mfma_f32_16x16x32_bf16 v[92:95], v[84:87], v[68:71], v[156:159]
	s_waitcnt lgkmcnt(1)
	v_mfma_f32_16x16x32_bf16 v[100:103], v[96:99], v[68:71], v[152:155]
	s_nop 2
	ds_read_b128 v[152:155], v200 offset:4608
	ds_read_b128 v[76:79], v200 offset:4672
	ds_read_b128 v[156:159], v200 offset:6912
	ds_read_b128 v[72:75], v200 offset:6976
	v_mfma_f32_16x16x32_bf16 v[112:115], v[214:217], v[218:221], v[112:115]
	v_mfma_f32_16x16x32_bf16 v[56:59], v[214:217], v[230:233], v[56:59]
	v_mfma_f32_16x16x32_bf16 v[40:43], v[214:217], v[234:237], v[40:43]
	s_waitcnt lgkmcnt(3)
	v_mfma_f32_16x16x32_bf16 v[148:151], v[152:155], v[68:71], v[148:151]
	s_waitcnt lgkmcnt(1)
	v_mfma_f32_16x16x32_bf16 v[68:71], v[156:159], v[68:71], v[144:147]
	s_nop 2
	ds_read_b128 v[144:147], v196 offset:39168
	ds_read_b128 v[214:217], v196 offset:39232
	s_waitcnt lgkmcnt(1)
	v_mfma_f32_16x16x32_bf16 v[140:143], v[84:87], v[144:147], v[140:143]
	v_mfma_f32_16x16x32_bf16 v[136:139], v[96:99], v[144:147], v[136:139]
	v_mfma_f32_16x16x32_bf16 v[132:135], v[152:155], v[144:147], v[132:135]
	v_mfma_f32_16x16x32_bf16 v[128:131], v[156:159], v[144:147], v[128:131]
	ds_read_b128 v[144:147], v196 offset:41472
	ds_read_b128 v[218:221], v196 offset:41536
	s_waitcnt lgkmcnt(1)
	v_mfma_f32_16x16x32_bf16 v[124:127], v[84:87], v[144:147], v[124:127]
	v_mfma_f32_16x16x32_bf16 v[120:123], v[96:99], v[144:147], v[120:123]
	v_mfma_f32_16x16x32_bf16 v[116:119], v[152:155], v[144:147], v[116:119]
	v_mfma_f32_16x16x32_bf16 v[112:115], v[156:159], v[144:147], v[112:115]
	ds_read_b128 v[144:147], v196 offset:43776
	ds_read_b128 v[222:225], v196 offset:43840
	s_waitcnt lgkmcnt(1)
	v_mfma_f32_16x16x32_bf16 v[108:111], v[84:87], v[144:147], v[108:111]
	v_mfma_f32_16x16x32_bf16 v[104:107], v[96:99], v[144:147], v[104:107]
	v_mfma_f32_16x16x32_bf16 v[4:7], v[152:155], v[144:147], v[4:7]
	v_mfma_f32_16x16x32_bf16 v[0:3], v[156:159], v[144:147], v[0:3]
	ds_read_b128 v[144:147], v196 offset:46080
	ds_read_b128 v[226:229], v196 offset:46144
	s_waitcnt lgkmcnt(1)
	v_mfma_f32_16x16x32_bf16 v[8:11], v[84:87], v[144:147], v[8:11]
	v_mfma_f32_16x16x32_bf16 v[12:15], v[96:99], v[144:147], v[12:15]
	v_mfma_f32_16x16x32_bf16 v[16:19], v[152:155], v[144:147], v[16:19]
	v_mfma_f32_16x16x32_bf16 v[20:23], v[156:159], v[144:147], v[20:23]
	ds_read_b128 v[144:147], v196 offset:48384
	ds_read_b128 v[230:233], v196 offset:48448
	s_waitcnt lgkmcnt(1)
	v_mfma_f32_16x16x32_bf16 v[24:27], v[84:87], v[144:147], v[24:27]
	v_mfma_f32_16x16x32_bf16 v[28:31], v[96:99], v[144:147], v[28:31]
	v_mfma_f32_16x16x32_bf16 v[60:63], v[152:155], v[144:147], v[60:63]
	v_mfma_f32_16x16x32_bf16 v[56:59], v[156:159], v[144:147], v[56:59]
	ds_read_b128 v[144:147], v196 offset:50688
	ds_read_b128 v[234:237], v196 offset:50752
	s_waitcnt lgkmcnt(1)
	v_mfma_f32_16x16x32_bf16 v[52:55], v[84:87], v[144:147], v[52:55]
	v_mfma_f32_16x16x32_bf16 v[48:51], v[96:99], v[144:147], v[48:51]
	v_mfma_f32_16x16x32_bf16 v[44:47], v[152:155], v[144:147], v[44:47]
	v_mfma_f32_16x16x32_bf16 v[40:43], v[156:159], v[144:147], v[40:43]
	ds_read_b128 v[144:147], v196 offset:52992
	ds_read_b128 v[238:241], v196 offset:53056
	s_waitcnt lgkmcnt(1)
	v_mfma_f32_16x16x32_bf16 v[242:245], v[152:155], v[144:147], v[64:67]
	v_mfma_f32_16x16x32_bf16 v[152:155], v[210:213], v[88:91], v[100:103]
	v_mfma_f32_16x16x32_bf16 v[100:103], v[76:79], v[222:225], v[4:7]
	s_nop 2
	v_lshl_add_u64 v[4:5], s[4:5], 0, v[192:193]
	v_mfma_f32_16x16x32_bf16 v[246:249], v[156:159], v[144:147], v[80:83]
	v_lshl_add_u64 v[6:7], s[50:51], 0, v[192:193]
	v_mfma_f32_16x16x32_bf16 v[156:159], v[206:209], v[88:91], v[92:95]
	v_mfma_f32_16x16x32_bf16 v[92:95], v[206:209], v[226:229], v[8:11]
	s_nop 2
	v_add_co_u32_e64 v8, s[4:5], s14, v4
	v_mfma_f32_16x16x32_bf16 v[36:39], v[84:87], v[144:147], v[36:39]
	s_nop 0
	v_addc_co_u32_e64 v9, s[4:5], 0, v5, s[4:5]
	v_mfma_f32_16x16x32_bf16 v[32:35], v[96:99], v[144:147], v[32:35]
	v_mfma_f32_16x16x32_bf16 v[148:151], v[76:79], v[88:91], v[148:151]
	v_mfma_f32_16x16x32_bf16 v[144:147], v[72:75], v[88:91], v[68:71]
	v_mfma_f32_16x16x32_bf16 v[88:91], v[210:213], v[226:229], v[12:15]
	s_nop 2
	v_add_co_u32_e64 v12, s[4:5], s15, v4
	v_mfma_f32_16x16x32_bf16 v[84:87], v[76:79], v[226:229], v[16:19]
	s_nop 0
	v_addc_co_u32_e64 v13, s[4:5], 0, v5, s[4:5]
	s_nop 0
	v_add_co_u32_e64 v16, s[4:5], s27, v4
	v_mfma_f32_16x16x32_bf16 v[80:83], v[72:75], v[226:229], v[20:23]
	s_nop 0
	v_addc_co_u32_e64 v17, s[4:5], 0, v5, s[4:5]
	s_nop 0
	v_add_co_u32_e64 v20, s[4:5], s14, v6
	v_mfma_f32_16x16x32_bf16 v[68:71], v[206:209], v[230:233], v[24:27]
	s_nop 0
	v_addc_co_u32_e64 v21, s[4:5], 0, v7, s[4:5]
	s_nop 0
	v_add_co_u32_e64 v24, s[4:5], s15, v6
	v_mfma_f32_16x16x32_bf16 v[64:67], v[210:213], v[230:233], v[28:31]
	s_nop 0
	v_addc_co_u32_e64 v25, s[4:5], 0, v7, s[4:5]
	s_nop 0
	v_add_co_u32_e64 v28, s[4:5], s27, v6
	v_mfma_f32_16x16x32_bf16 v[96:99], v[72:75], v[222:225], v[0:3]
	s_nop 0
	v_addc_co_u32_e64 v29, s[4:5], 0, v7, s[4:5]
	s_nop 0
	global_load_dwordx4 v[0:3], v[6:7], off
	s_nop 0
	global_load_dwordx4 v[4:7], v[4:5], off
	s_nop 0
	global_load_dwordx4 v[8:11], v[8:9], off
	s_nop 0
	global_load_dwordx4 v[12:15], v[12:13], off
	s_nop 0
	global_load_dwordx4 v[16:19], v[16:17], off
	s_nop 0
	global_load_dwordx4 v[20:23], v[20:21], off
	s_nop 0
	global_load_dwordx4 v[24:27], v[24:25], off
	v_mfma_f32_16x16x32_bf16 v[140:143], v[206:209], v[214:217], v[140:143]
	global_load_dwordx4 v[28:31], v[28:29], off
	s_waitcnt vmcnt(14)
	ds_write_b128 v194, v[160:163]
	ds_write_b128 v195, v[164:167]
	s_waitcnt vmcnt(13)
	ds_write_b128 v194, v[168:171] offset:9216
	s_waitcnt vmcnt(12)
	ds_write_b128 v194, v[172:175] offset:18432
	s_waitcnt vmcnt(11)
	ds_write_b128 v194, v[176:179] offset:27648
	s_waitcnt vmcnt(10)
	ds_write_b128 v195, v[180:183] offset:9216
	s_waitcnt vmcnt(9)
	ds_write_b128 v195, v[184:187] offset:18432
	s_waitcnt vmcnt(8)
	ds_write_b128 v195, v[188:191] offset:27648
	s_waitcnt lgkmcnt(0)
	v_mfma_f32_16x16x32_bf16 v[136:139], v[210:213], v[214:217], v[136:139]
	s_barrier
	v_mfma_f32_16x16x32_bf16 v[132:135], v[76:79], v[214:217], v[132:135]
	v_mfma_f32_16x16x32_bf16 v[128:131], v[72:75], v[214:217], v[128:131]
	v_mfma_f32_16x16x32_bf16 v[124:127], v[206:209], v[218:221], v[124:127]
	v_mfma_f32_16x16x32_bf16 v[120:123], v[210:213], v[218:221], v[120:123]
	v_mfma_f32_16x16x32_bf16 v[116:119], v[76:79], v[218:221], v[116:119]
	v_mfma_f32_16x16x32_bf16 v[112:115], v[72:75], v[218:221], v[112:115]
	v_mfma_f32_16x16x32_bf16 v[108:111], v[206:209], v[222:225], v[108:111]
	v_mfma_f32_16x16x32_bf16 v[104:107], v[210:213], v[222:225], v[104:107]
	v_mfma_f32_16x16x32_bf16 v[60:63], v[76:79], v[230:233], v[60:63]
	v_mfma_f32_16x16x32_bf16 v[56:59], v[72:75], v[230:233], v[56:59]
	v_mfma_f32_16x16x32_bf16 v[52:55], v[206:209], v[234:237], v[52:55]
	v_mfma_f32_16x16x32_bf16 v[48:51], v[210:213], v[234:237], v[48:51]
	v_mfma_f32_16x16x32_bf16 v[44:47], v[76:79], v[234:237], v[44:47]
	v_mfma_f32_16x16x32_bf16 v[40:43], v[72:75], v[234:237], v[40:43]
	v_mfma_f32_16x16x32_bf16 v[36:39], v[206:209], v[238:241], v[36:39]
	v_mfma_f32_16x16x32_bf16 v[32:35], v[210:213], v[238:241], v[32:35]
	v_mfma_f32_16x16x32_bf16 v[76:79], v[76:79], v[238:241], v[242:245]
	v_mfma_f32_16x16x32_bf16 v[72:75], v[72:75], v[238:241], v[246:249]
	s_cbranch_vccz .LBB0_195
	s_mul_i32 s98, s26, 0x1040
	s_lshl_b32 s99, s28, 1
	s_add_u32 s98, s98, s99
	s_add_u32 s100, s16, s98
	s_addc_u32 s101, s17, 0
	v_and_b32_e32 v160, 15, v197
	v_and_b32_e32 v161, 0x80, v201
	v_add_u32_e32 v160, v160, v161
	v_mul_u32_u24_e32 v160, 0x1040, v160
	v_and_b32_e32 v161, 0xc0, v197
	v_lshl_add_u32 v160, v161, 1, v160
	v_and_b32_e32 v161, 4, v201
	v_lshl_add_u32 v160, v161, 3, v160
	v_and_b32_e32 v161, 8, v201
	v_lshl_add_u32 v160, v161, 1, v160
	v_cvt_pk_bf16_f32 v156, v156, v157
	v_cvt_pk_bf16_f32 v157, v158, v159
	v_cvt_pk_bf16_f32 v158, v152, v153
	v_cvt_pk_bf16_f32 v159, v154, v155
	v_cvt_pk_bf16_f32 v148, v148, v149
	v_cvt_pk_bf16_f32 v149, v150, v151
	v_cvt_pk_bf16_f32 v150, v144, v145
	v_cvt_pk_bf16_f32 v151, v146, v147
	v_permlane16_swap_b32_e32 v156, v158
	v_permlane16_swap_b32_e32 v157, v159
	v_permlane16_swap_b32_e32 v148, v150
	v_permlane16_swap_b32_e32 v149, v151
	global_store_dwordx4 v160, v[156:159], s[100:101] sc1
	global_store_dwordx4 v160, v[148:151], s[100:101] offset:64 sc1
	s_add_u32 s100, s100, 0x10400
	s_addc_u32 s101, s101, 0
	v_cvt_pk_bf16_f32 v140, v140, v141
	v_cvt_pk_bf16_f32 v141, v142, v143
	v_cvt_pk_bf16_f32 v142, v136, v137
	v_cvt_pk_bf16_f32 v143, v138, v139
	v_cvt_pk_bf16_f32 v132, v132, v133
	v_cvt_pk_bf16_f32 v133, v134, v135
	v_cvt_pk_bf16_f32 v134, v128, v129
	v_cvt_pk_bf16_f32 v135, v130, v131
	v_permlane16_swap_b32_e32 v140, v142
	v_permlane16_swap_b32_e32 v141, v143
	v_permlane16_swap_b32_e32 v132, v134
	v_permlane16_swap_b32_e32 v133, v135
	global_store_dwordx4 v160, v[140:143], s[100:101] sc1
	global_store_dwordx4 v160, v[132:135], s[100:101] offset:64 sc1
	s_add_u32 s100, s100, 0x10400
	s_addc_u32 s101, s101, 0
	v_cvt_pk_bf16_f32 v124, v124, v125
	v_cvt_pk_bf16_f32 v125, v126, v127
	v_cvt_pk_bf16_f32 v126, v120, v121
	v_cvt_pk_bf16_f32 v127, v122, v123
	v_cvt_pk_bf16_f32 v116, v116, v117
	v_cvt_pk_bf16_f32 v117, v118, v119
	v_cvt_pk_bf16_f32 v118, v112, v113
	v_cvt_pk_bf16_f32 v119, v114, v115
	v_permlane16_swap_b32_e32 v124, v126
	v_permlane16_swap_b32_e32 v125, v127
	v_permlane16_swap_b32_e32 v116, v118
	v_permlane16_swap_b32_e32 v117, v119
	global_store_dwordx4 v160, v[124:127], s[100:101] sc1
	global_store_dwordx4 v160, v[116:119], s[100:101] offset:64 sc1
	s_add_u32 s100, s100, 0x10400
	s_addc_u32 s101, s101, 0
	v_cvt_pk_bf16_f32 v108, v108, v109
	v_cvt_pk_bf16_f32 v109, v110, v111
	v_cvt_pk_bf16_f32 v110, v104, v105
	v_cvt_pk_bf16_f32 v111, v106, v107
	v_cvt_pk_bf16_f32 v100, v100, v101
	v_cvt_pk_bf16_f32 v101, v102, v103
	v_cvt_pk_bf16_f32 v102, v96, v97
	v_cvt_pk_bf16_f32 v103, v98, v99
	v_permlane16_swap_b32_e32 v108, v110
	v_permlane16_swap_b32_e32 v109, v111
	v_permlane16_swap_b32_e32 v100, v102
	v_permlane16_swap_b32_e32 v101, v103
	global_store_dwordx4 v160, v[108:111], s[100:101] sc1
	global_store_dwordx4 v160, v[100:103], s[100:101] offset:64 sc1
	s_add_u32 s100, s100, 0x10400
	s_addc_u32 s101, s101, 0
	v_cvt_pk_bf16_f32 v92, v92, v93
	v_cvt_pk_bf16_f32 v93, v94, v95
	v_cvt_pk_bf16_f32 v94, v88, v89
	v_cvt_pk_bf16_f32 v95, v90, v91
	v_cvt_pk_bf16_f32 v84, v84, v85
	v_cvt_pk_bf16_f32 v85, v86, v87
	v_cvt_pk_bf16_f32 v86, v80, v81
	v_cvt_pk_bf16_f32 v87, v82, v83
	v_permlane16_swap_b32_e32 v92, v94
	v_permlane16_swap_b32_e32 v93, v95
	v_permlane16_swap_b32_e32 v84, v86
	v_permlane16_swap_b32_e32 v85, v87
	global_store_dwordx4 v160, v[92:95], s[100:101] sc1
	global_store_dwordx4 v160, v[84:87], s[100:101] offset:64 sc1
	s_add_u32 s100, s100, 0x10400
	s_addc_u32 s101, s101, 0
	v_cvt_pk_bf16_f32 v68, v68, v69
	v_cvt_pk_bf16_f32 v69, v70, v71
	v_cvt_pk_bf16_f32 v70, v64, v65
	v_cvt_pk_bf16_f32 v71, v66, v67
	v_cvt_pk_bf16_f32 v60, v60, v61
	v_cvt_pk_bf16_f32 v61, v62, v63
	v_cvt_pk_bf16_f32 v62, v56, v57
	v_cvt_pk_bf16_f32 v63, v58, v59
	v_permlane16_swap_b32_e32 v68, v70
	v_permlane16_swap_b32_e32 v69, v71
	v_permlane16_swap_b32_e32 v60, v62
	v_permlane16_swap_b32_e32 v61, v63
	global_store_dwordx4 v160, v[68:71], s[100:101] sc1
	global_store_dwordx4 v160, v[60:63], s[100:101] offset:64 sc1
	s_add_u32 s100, s100, 0x10400
	s_addc_u32 s101, s101, 0
	v_cvt_pk_bf16_f32 v52, v52, v53
	v_cvt_pk_bf16_f32 v53, v54, v55
	v_cvt_pk_bf16_f32 v54, v48, v49
	v_cvt_pk_bf16_f32 v55, v50, v51
	v_cvt_pk_bf16_f32 v44, v44, v45
	v_cvt_pk_bf16_f32 v45, v46, v47
	v_cvt_pk_bf16_f32 v46, v40, v41
	v_cvt_pk_bf16_f32 v47, v42, v43
	v_permlane16_swap_b32_e32 v52, v54
	v_permlane16_swap_b32_e32 v53, v55
	v_permlane16_swap_b32_e32 v44, v46
	v_permlane16_swap_b32_e32 v45, v47
	global_store_dwordx4 v160, v[52:55], s[100:101] sc1
	global_store_dwordx4 v160, v[44:47], s[100:101] offset:64 sc1
	s_add_u32 s100, s100, 0x10400
	s_addc_u32 s101, s101, 0
	v_cvt_pk_bf16_f32 v36, v36, v37
	v_cvt_pk_bf16_f32 v37, v38, v39
	v_cvt_pk_bf16_f32 v38, v32, v33
	v_cvt_pk_bf16_f32 v39, v34, v35
	v_cvt_pk_bf16_f32 v76, v76, v77
	v_cvt_pk_bf16_f32 v77, v78, v79
	v_cvt_pk_bf16_f32 v78, v72, v73
	v_cvt_pk_bf16_f32 v79, v74, v75
	v_permlane16_swap_b32_e32 v36, v38
	v_permlane16_swap_b32_e32 v37, v39
	v_permlane16_swap_b32_e32 v76, v78
	v_permlane16_swap_b32_e32 v77, v79
	global_store_dwordx4 v160, v[36:39], s[100:101] sc1
	global_store_dwordx4 v160, v[76:79], s[100:101] offset:64 sc1
	s_and_b64 vcc, exec, s[20:21]
	s_mov_b32 s28, s24
	s_mov_b32 s26, s22
	s_mov_b64 s[30:31], s[12:13]
	s_mov_b64 s[4:5], s[10:11]
	s_cbranch_vccz .LBB0_192

.LBB0_1020:
	ds_read_b128 v[160:163], v202
	ds_read_b128 v[164:167], v203
	ds_read_b128 v[180:183], v203 offset:64
	ds_read_b128 v[168:171], v202 offset:64
	ds_read_b128 v[172:175], v203 offset:2304
	ds_read_b128 v[192:195], v203 offset:2368
	ds_read_b128 v[176:179], v203 offset:4608
	ds_read_b128 v[210:213], v203 offset:4672
	ds_read_b128 v[184:187], v203 offset:6912
	ds_read_b128 v[214:217], v203 offset:6976
	s_waitcnt lgkmcnt(8)
	v_mfma_f32_16x16x32_bf16 v[156:159], v[164:167], v[160:163], v[156:159]
	s_add_i32 s81, s80, 2
	s_add_u32 s82, s58, 0xffffff80
	s_addc_u32 s83, s59, -1
	s_waitcnt lgkmcnt(5)
	v_mfma_f32_16x16x32_bf16 v[152:155], v[172:175], v[160:163], v[152:155]
	s_add_u32 s84, s60, 0xffffff80
	s_addc_u32 s85, s61, -1
	s_cmp_lt_u32 s80, 6
	s_waitcnt lgkmcnt(3)
	v_mfma_f32_16x16x32_bf16 v[148:151], v[176:179], v[160:163], v[148:151]
	s_cselect_b32 s82, s82, s42
	s_cselect_b32 s83, s83, s43
	s_cselect_b32 s84, s84, s44
	s_waitcnt lgkmcnt(1)
	v_mfma_f32_16x16x32_bf16 v[144:147], v[184:187], v[160:163], v[144:147]
	ds_read_b128 v[160:163], v202 offset:2304
	ds_read_b128 v[188:191], v202 offset:2368
	s_cselect_b32 s85, s85, s45
	s_cmp_lt_u32 s80, 5
	s_waitcnt lgkmcnt(1)
	v_mfma_f32_16x16x32_bf16 v[140:143], v[164:167], v[160:163], v[140:143]
	v_mfma_f32_16x16x32_bf16 v[136:139], v[172:175], v[160:163], v[136:139]
	v_mfma_f32_16x16x32_bf16 v[132:135], v[176:179], v[160:163], v[132:135]
	v_mfma_f32_16x16x32_bf16 v[128:131], v[184:187], v[160:163], v[128:131]
	ds_read_b128 v[160:163], v202 offset:4608
	ds_read_b128 v[218:221], v202 offset:4672
	s_waitcnt lgkmcnt(1)
	v_mfma_f32_16x16x32_bf16 v[124:127], v[164:167], v[160:163], v[124:127]
	v_mfma_f32_16x16x32_bf16 v[120:123], v[172:175], v[160:163], v[120:123]
	v_mfma_f32_16x16x32_bf16 v[116:119], v[176:179], v[160:163], v[116:119]
	v_mfma_f32_16x16x32_bf16 v[112:115], v[184:187], v[160:163], v[112:115]
	ds_read_b128 v[160:163], v202 offset:6912
	ds_read_b128 v[222:225], v202 offset:6976
	s_waitcnt lgkmcnt(1)
	v_mfma_f32_16x16x32_bf16 v[108:111], v[164:167], v[160:163], v[108:111]
	v_mfma_f32_16x16x32_bf16 v[104:107], v[172:175], v[160:163], v[104:107]
	v_mfma_f32_16x16x32_bf16 v[100:103], v[176:179], v[160:163], v[100:103]
	v_mfma_f32_16x16x32_bf16 v[96:99], v[184:187], v[160:163], v[96:99]
	ds_read_b128 v[160:163], v202 offset:9216
	ds_read_b128 v[226:229], v202 offset:9280
	s_waitcnt lgkmcnt(1)
	v_mfma_f32_16x16x32_bf16 v[92:95], v[164:167], v[160:163], v[92:95]
	v_mfma_f32_16x16x32_bf16 v[88:91], v[172:175], v[160:163], v[88:91]
	v_mfma_f32_16x16x32_bf16 v[80:83], v[176:179], v[160:163], v[80:83]
	v_mfma_f32_16x16x32_bf16 v[84:87], v[184:187], v[160:163], v[84:87]
	ds_read_b128 v[160:163], v202 offset:11520
	ds_read_b128 v[230:233], v202 offset:11584
	s_waitcnt lgkmcnt(1)
	v_mfma_f32_16x16x32_bf16 v[76:79], v[164:167], v[160:163], v[76:79]
	v_mfma_f32_16x16x32_bf16 v[72:75], v[172:175], v[160:163], v[72:75]
	v_mfma_f32_16x16x32_bf16 v[68:71], v[176:179], v[160:163], v[68:71]
	v_mfma_f32_16x16x32_bf16 v[64:67], v[184:187], v[160:163], v[64:67]
	ds_read_b128 v[160:163], v202 offset:13824
	ds_read_b128 v[234:237], v202 offset:13888
	s_waitcnt lgkmcnt(1)
	v_mfma_f32_16x16x32_bf16 v[60:63], v[164:167], v[160:163], v[60:63]
	v_mfma_f32_16x16x32_bf16 v[56:59], v[172:175], v[160:163], v[56:59]
	v_mfma_f32_16x16x32_bf16 v[52:55], v[176:179], v[160:163], v[52:55]
	v_mfma_f32_16x16x32_bf16 v[48:51], v[184:187], v[160:163], v[48:51]
	ds_read_b128 v[160:163], v202 offset:16128
	ds_read_b128 v[238:241], v202 offset:16192
	s_waitcnt vmcnt(6)
	ds_write_b128 v200, v[4:7] offset:36864
	s_waitcnt vmcnt(5)
	ds_write_b128 v200, v[8:11] offset:46080
	s_waitcnt vmcnt(4)
	ds_write_b128 v200, v[12:15] offset:55296
	s_waitcnt vmcnt(3)
	ds_write_b128 v200, v[16:19] offset:64512
	v_mfma_f32_16x16x32_bf16 v[16:19], v[210:213], v[226:229], v[80:83]
	s_waitcnt vmcnt(3)
	ds_write_b128 v208, v[0:3]
	s_waitcnt vmcnt(2)
	ds_write_b128 v208, v[20:23] offset:9216
	s_waitcnt vmcnt(1)
	ds_write_b128 v208, v[24:27] offset:18432
	v_lshl_add_u64 v[80:81], s[82:83], 0, v[196:197]
	s_waitcnt vmcnt(0)
	ds_write_b128 v208, v[28:31] offset:27648
	v_mfma_f32_16x16x32_bf16 v[24:27], v[180:183], v[230:233], v[76:79]
	v_lshl_add_u64 v[82:83], s[84:85], 0, v[196:197]
	s_cselect_b32 s82, s58, s49
	s_cselect_b32 s83, s59, s77
	v_add_co_u32_e32 v76, vcc, s57, v80
	v_mfma_f32_16x16x32_bf16 v[28:31], v[192:195], v[230:233], v[72:75]
	s_nop 0
	v_addc_co_u32_e32 v77, vcc, 0, v81, vcc
	s_cselect_b32 s84, s60, s78
	v_add_co_u32_e32 v72, vcc, s63, v80
	s_waitcnt lgkmcnt(9)
	v_mfma_f32_16x16x32_bf16 v[40:43], v[164:167], v[160:163], v[40:43]
	v_addc_co_u32_e32 v73, vcc, 0, v81, vcc
	v_add_co_u32_e32 v74, vcc, s64, v80
	v_mfma_f32_16x16x32_bf16 v[36:39], v[172:175], v[160:163], v[36:39]
	s_nop 0
	v_addc_co_u32_e32 v75, vcc, 0, v81, vcc
	v_add_co_u32_e32 v78, vcc, s57, v82
	v_mfma_f32_16x16x32_bf16 v[32:35], v[176:179], v[160:163], v[32:35]
	s_nop 0
	v_addc_co_u32_e32 v79, vcc, 0, v83, vcc
	global_load_dwordx4 v[164:167], v[82:83], off
	v_mfma_f32_16x16x32_bf16 v[44:47], v[184:187], v[160:163], v[44:47]
	global_load_dwordx4 v[160:163], v[80:81], off
	v_add_co_u32_e32 v80, vcc, s63, v82
	v_mfma_f32_16x16x32_bf16 v[156:159], v[180:183], v[168:171], v[156:159]
	s_nop 0
	v_addc_co_u32_e32 v81, vcc, 0, v83, vcc
	v_add_co_u32_e32 v82, vcc, s64, v82
	v_mfma_f32_16x16x32_bf16 v[152:155], v[192:195], v[168:171], v[152:155]
	s_nop 0
	v_addc_co_u32_e32 v83, vcc, 0, v83, vcc
	s_cselect_b32 s85, s61, s79
	v_mfma_f32_16x16x32_bf16 v[148:151], v[210:213], v[168:171], v[148:151]
	s_add_u32 s60, s60, 0x100
	s_addc_u32 s61, s61, 0
	s_add_u32 s58, s58, 0x100
	v_mfma_f32_16x16x32_bf16 v[144:147], v[214:217], v[168:171], v[144:147]
	global_load_dwordx4 v[168:171], v[76:77], off
	global_load_dwordx4 v[172:175], v[72:73], off
	global_load_dwordx4 v[176:179], v[74:75], off
	s_addc_u32 s59, s59, 0
	s_cmp_gt_u32 s80, 5
	v_mfma_f32_16x16x32_bf16 v[140:143], v[180:183], v[188:191], v[140:143]
	s_mov_b32 s80, s81
	v_mfma_f32_16x16x32_bf16 v[136:139], v[192:195], v[188:191], v[136:139]
	v_mfma_f32_16x16x32_bf16 v[132:135], v[210:213], v[188:191], v[132:135]
	v_mfma_f32_16x16x32_bf16 v[128:131], v[214:217], v[188:191], v[128:131]
	v_mfma_f32_16x16x32_bf16 v[124:127], v[180:183], v[218:221], v[124:127]
	v_mfma_f32_16x16x32_bf16 v[108:111], v[180:183], v[222:225], v[108:111]
	v_mfma_f32_16x16x32_bf16 v[0:3], v[180:183], v[226:229], v[92:95]
	v_mfma_f32_16x16x32_bf16 v[60:63], v[180:183], v[234:237], v[60:63]
	s_waitcnt lgkmcnt(8)
	v_mfma_f32_16x16x32_bf16 v[40:43], v[180:183], v[238:241], v[40:43]
	global_load_dwordx4 v[180:183], v[78:79], off
	global_load_dwordx4 v[184:187], v[80:81], off
	global_load_dwordx4 v[188:191], v[82:83], off
	s_waitcnt lgkmcnt(0)
	s_barrier
	ds_read_b128 v[72:75], v202 offset:36864
	v_mfma_f32_16x16x32_bf16 v[116:119], v[210:213], v[218:221], v[116:119]
	v_mfma_f32_16x16x32_bf16 v[112:115], v[214:217], v[218:221], v[112:115]
	v_mfma_f32_16x16x32_bf16 v[4:7], v[210:213], v[222:225], v[100:103]
	v_mfma_f32_16x16x32_bf16 v[8:11], v[214:217], v[222:225], v[96:99]
	v_mfma_f32_16x16x32_bf16 v[20:23], v[214:217], v[226:229], v[84:87]
	v_mfma_f32_16x16x32_bf16 v[68:71], v[210:213], v[230:233], v[68:71]
	v_mfma_f32_16x16x32_bf16 v[64:67], v[214:217], v[230:233], v[64:67]
	v_mfma_f32_16x16x32_bf16 v[52:55], v[210:213], v[234:237], v[52:55]
	v_mfma_f32_16x16x32_bf16 v[48:51], v[214:217], v[234:237], v[48:51]
	v_mfma_f32_16x16x32_bf16 v[32:35], v[210:213], v[238:241], v[32:35]
	ds_read_b128 v[80:83], v209
	ds_read_b128 v[210:213], v209 offset:64
	ds_read_b128 v[84:87], v202 offset:36928
	v_mfma_f32_16x16x32_bf16 v[76:79], v[214:217], v[238:241], v[44:47]
	ds_read_b128 v[92:95], v209 offset:2304
	ds_read_b128 v[214:217], v209 offset:2368
	v_mfma_f32_16x16x32_bf16 v[120:123], v[192:195], v[218:221], v[120:123]
	ds_read_b128 v[100:103], v209 offset:4608
	ds_read_b128 v[218:221], v209 offset:4672
	s_waitcnt lgkmcnt(3)
	v_mfma_f32_16x16x32_bf16 v[96:99], v[92:95], v[72:75], v[152:155]
	s_nop 2
	ds_read_b128 v[152:155], v209 offset:6912
	ds_read_b128 v[44:47], v209 offset:6976
	v_mfma_f32_16x16x32_bf16 v[104:107], v[192:195], v[222:225], v[104:107]
	v_mfma_f32_16x16x32_bf16 v[12:15], v[192:195], v[226:229], v[88:91]
	v_mfma_f32_16x16x32_bf16 v[88:91], v[80:83], v[72:75], v[156:159]
	s_waitcnt lgkmcnt(3)
	v_mfma_f32_16x16x32_bf16 v[148:151], v[100:103], v[72:75], v[148:151]
	s_waitcnt lgkmcnt(1)
	v_mfma_f32_16x16x32_bf16 v[72:75], v[152:155], v[72:75], v[144:147]
	s_nop 2
	ds_read_b128 v[144:147], v202 offset:39168
	ds_read_b128 v[222:225], v202 offset:39232
	s_waitcnt lgkmcnt(1)
	v_mfma_f32_16x16x32_bf16 v[140:143], v[80:83], v[144:147], v[140:143]
	v_mfma_f32_16x16x32_bf16 v[136:139], v[92:95], v[144:147], v[136:139]
	v_mfma_f32_16x16x32_bf16 v[132:135], v[100:103], v[144:147], v[132:135]
	v_mfma_f32_16x16x32_bf16 v[128:131], v[152:155], v[144:147], v[128:131]
	ds_read_b128 v[144:147], v202 offset:41472
	ds_read_b128 v[226:229], v202 offset:41536
	s_waitcnt lgkmcnt(1)
	v_mfma_f32_16x16x32_bf16 v[124:127], v[80:83], v[144:147], v[124:127]
	v_mfma_f32_16x16x32_bf16 v[120:123], v[92:95], v[144:147], v[120:123]
	v_mfma_f32_16x16x32_bf16 v[116:119], v[100:103], v[144:147], v[116:119]
	v_mfma_f32_16x16x32_bf16 v[112:115], v[152:155], v[144:147], v[112:115]
	ds_read_b128 v[144:147], v202 offset:43776
	ds_read_b128 v[230:233], v202 offset:43840
	v_mfma_f32_16x16x32_bf16 v[56:59], v[192:195], v[234:237], v[56:59]
	s_waitcnt lgkmcnt(1)
	v_mfma_f32_16x16x32_bf16 v[108:111], v[80:83], v[144:147], v[108:111]
	v_mfma_f32_16x16x32_bf16 v[104:107], v[92:95], v[144:147], v[104:107]
	v_mfma_f32_16x16x32_bf16 v[4:7], v[100:103], v[144:147], v[4:7]
	v_mfma_f32_16x16x32_bf16 v[8:11], v[152:155], v[144:147], v[8:11]
	ds_read_b128 v[144:147], v202 offset:46080
	ds_read_b128 v[234:237], v202 offset:46144
	v_mfma_f32_16x16x32_bf16 v[36:39], v[192:195], v[238:241], v[36:39]
	s_waitcnt lgkmcnt(1)
	v_mfma_f32_16x16x32_bf16 v[0:3], v[80:83], v[144:147], v[0:3]
	v_mfma_f32_16x16x32_bf16 v[12:15], v[92:95], v[144:147], v[12:15]
	v_mfma_f32_16x16x32_bf16 v[16:19], v[100:103], v[144:147], v[16:19]
	v_mfma_f32_16x16x32_bf16 v[20:23], v[152:155], v[144:147], v[20:23]
	ds_read_b128 v[144:147], v202 offset:48384
	ds_read_b128 v[238:241], v202 offset:48448
	s_waitcnt lgkmcnt(1)
	v_mfma_f32_16x16x32_bf16 v[24:27], v[80:83], v[144:147], v[24:27]
	v_mfma_f32_16x16x32_bf16 v[28:31], v[92:95], v[144:147], v[28:31]
	v_mfma_f32_16x16x32_bf16 v[68:71], v[100:103], v[144:147], v[68:71]
	v_mfma_f32_16x16x32_bf16 v[64:67], v[152:155], v[144:147], v[64:67]
	ds_read_b128 v[144:147], v202 offset:50688
	ds_read_b128 v[242:245], v202 offset:50752
	s_waitcnt lgkmcnt(1)
	v_mfma_f32_16x16x32_bf16 v[60:63], v[80:83], v[144:147], v[60:63]
	v_mfma_f32_16x16x32_bf16 v[56:59], v[92:95], v[144:147], v[56:59]
	v_mfma_f32_16x16x32_bf16 v[52:55], v[100:103], v[144:147], v[52:55]
	v_mfma_f32_16x16x32_bf16 v[48:51], v[152:155], v[144:147], v[48:51]
	ds_read_b128 v[144:147], v202 offset:52992
	ds_read_b128 v[192:195], v202 offset:53056
	s_waitcnt lgkmcnt(1)
	v_mfma_f32_16x16x32_bf16 v[32:35], v[100:103], v[144:147], v[32:35]
	v_mfma_f32_16x16x32_bf16 v[100:103], v[218:221], v[230:233], v[4:7]
	s_nop 2
	v_lshl_add_u64 v[4:5], s[82:83], 0, v[196:197]
	v_mfma_f32_16x16x32_bf16 v[246:249], v[152:155], v[144:147], v[76:79]
	v_lshl_add_u64 v[6:7], s[84:85], 0, v[196:197]
	v_mfma_f32_16x16x32_bf16 v[152:155], v[214:217], v[84:87], v[96:99]
	v_mfma_f32_16x16x32_bf16 v[96:99], v[44:47], v[230:233], v[8:11]
	s_nop 2
	v_add_co_u32_e32 v8, vcc, s57, v4
	v_mfma_f32_16x16x32_bf16 v[156:159], v[210:213], v[84:87], v[88:91]
	s_nop 0
	v_addc_co_u32_e32 v9, vcc, 0, v5, vcc
	v_mfma_f32_16x16x32_bf16 v[88:91], v[214:217], v[234:237], v[12:15]
	s_nop 2
	v_add_co_u32_e32 v12, vcc, s63, v4
	v_mfma_f32_16x16x32_bf16 v[40:43], v[80:83], v[144:147], v[40:43]
	s_nop 0
	v_addc_co_u32_e32 v13, vcc, 0, v5, vcc
	v_mfma_f32_16x16x32_bf16 v[80:83], v[218:221], v[234:237], v[16:19]
	s_nop 2
	v_add_co_u32_e32 v16, vcc, s64, v4
	v_mfma_f32_16x16x32_bf16 v[36:39], v[92:95], v[144:147], v[36:39]
	s_nop 0
	v_addc_co_u32_e32 v17, vcc, 0, v5, vcc
	v_mfma_f32_16x16x32_bf16 v[148:151], v[218:221], v[84:87], v[148:151]
	v_mfma_f32_16x16x32_bf16 v[144:147], v[44:47], v[84:87], v[72:75]
	v_mfma_f32_16x16x32_bf16 v[84:87], v[44:47], v[234:237], v[20:23]
	s_nop 2
	v_add_co_u32_e32 v20, vcc, s57, v6
	v_mfma_f32_16x16x32_bf16 v[76:79], v[210:213], v[238:241], v[24:27]
	s_nop 0
	v_addc_co_u32_e32 v21, vcc, 0, v7, vcc
	s_nop 0
	v_add_co_u32_e32 v24, vcc, s63, v6
	v_mfma_f32_16x16x32_bf16 v[72:75], v[214:217], v[238:241], v[28:31]
	s_nop 0
	v_addc_co_u32_e32 v25, vcc, 0, v7, vcc
	s_nop 0
	v_add_co_u32_e32 v28, vcc, s64, v6
	v_mfma_f32_16x16x32_bf16 v[92:95], v[210:213], v[234:237], v[0:3]
	s_nop 0
	v_addc_co_u32_e32 v29, vcc, 0, v7, vcc
	s_nop 0
	global_load_dwordx4 v[0:3], v[6:7], off
	s_nop 0
	global_load_dwordx4 v[4:7], v[4:5], off
	s_nop 0
	global_load_dwordx4 v[8:11], v[8:9], off
	s_nop 0
	global_load_dwordx4 v[12:15], v[12:13], off
	s_nop 0
	global_load_dwordx4 v[16:19], v[16:17], off
	s_nop 0
	global_load_dwordx4 v[20:23], v[20:21], off
	s_nop 0
	global_load_dwordx4 v[24:27], v[24:25], off
	v_mfma_f32_16x16x32_bf16 v[140:143], v[210:213], v[222:225], v[140:143]
	global_load_dwordx4 v[28:31], v[28:29], off
	s_waitcnt vmcnt(14)
	ds_write_b128 v200, v[160:163]
	ds_write_b128 v207, v[164:167]
	s_waitcnt vmcnt(13)
	ds_write_b128 v200, v[168:171] offset:9216
	s_waitcnt vmcnt(12)
	ds_write_b128 v200, v[172:175] offset:18432
	s_waitcnt vmcnt(11)
	ds_write_b128 v200, v[176:179] offset:27648
	s_waitcnt vmcnt(10)
	ds_write_b128 v207, v[180:183] offset:9216
	s_waitcnt vmcnt(9)
	ds_write_b128 v207, v[184:187] offset:18432
	s_waitcnt vmcnt(8)
	ds_write_b128 v207, v[188:191] offset:27648
	s_waitcnt lgkmcnt(0)
	v_mfma_f32_16x16x32_bf16 v[136:139], v[214:217], v[222:225], v[136:139]
	s_barrier
	v_mfma_f32_16x16x32_bf16 v[132:135], v[218:221], v[222:225], v[132:135]
	v_mfma_f32_16x16x32_bf16 v[128:131], v[44:47], v[222:225], v[128:131]
	v_mfma_f32_16x16x32_bf16 v[124:127], v[210:213], v[226:229], v[124:127]
	v_mfma_f32_16x16x32_bf16 v[120:123], v[214:217], v[226:229], v[120:123]
	v_mfma_f32_16x16x32_bf16 v[116:119], v[218:221], v[226:229], v[116:119]
	v_mfma_f32_16x16x32_bf16 v[112:115], v[44:47], v[226:229], v[112:115]
	v_mfma_f32_16x16x32_bf16 v[108:111], v[210:213], v[230:233], v[108:111]
	v_mfma_f32_16x16x32_bf16 v[104:107], v[214:217], v[230:233], v[104:107]
	v_mfma_f32_16x16x32_bf16 v[68:71], v[218:221], v[238:241], v[68:71]
	v_mfma_f32_16x16x32_bf16 v[64:67], v[44:47], v[238:241], v[64:67]
	v_mfma_f32_16x16x32_bf16 v[60:63], v[210:213], v[242:245], v[60:63]
	v_mfma_f32_16x16x32_bf16 v[56:59], v[214:217], v[242:245], v[56:59]
	v_mfma_f32_16x16x32_bf16 v[52:55], v[218:221], v[242:245], v[52:55]
	v_mfma_f32_16x16x32_bf16 v[48:51], v[44:47], v[242:245], v[48:51]
	v_mfma_f32_16x16x32_bf16 v[40:43], v[210:213], v[192:195], v[40:43]
	v_mfma_f32_16x16x32_bf16 v[36:39], v[214:217], v[192:195], v[36:39]
	v_mfma_f32_16x16x32_bf16 v[32:35], v[218:221], v[192:195], v[32:35]
	v_mfma_f32_16x16x32_bf16 v[44:47], v[44:47], v[192:195], v[246:249]
	s_cbranch_scc0 .LBB0_1020
	s_cmp_eq_u32 s56, 0
	s_mov_b32 s99, 0x28c4000
	s_cselect_b32 s99, s99, 0x38c4000
	s_lshl_b32 s98, s76, 11
	s_lshl_b32 s100, s75, 1
	s_add_u32 s98, s98, s100
	s_add_u32 s98, s98, s99
	s_add_u32 s100, s34, s98
	s_addc_u32 s101, s35, 0
	v_and_b32_e32 v160, 15, v206
	v_and_b32_e32 v161, 0x80, v201
	v_add_u32_e32 v160, v160, v161
	v_lshlrev_b32_e32 v160, 11, v160
	v_and_b32_e32 v161, 0xc0, v206
	v_lshl_add_u32 v160, v161, 1, v160
	v_and_b32_e32 v161, 4, v201
	v_lshl_add_u32 v160, v161, 3, v160
	v_and_b32_e32 v161, 8, v201
	v_lshl_add_u32 v160, v161, 1, v160
	v_cvt_pk_bf16_f32 v156, v156, v157
	v_cvt_pk_bf16_f32 v157, v158, v159
	v_cvt_pk_bf16_f32 v158, v152, v153
	v_cvt_pk_bf16_f32 v159, v154, v155
	v_cvt_pk_bf16_f32 v148, v148, v149
	v_cvt_pk_bf16_f32 v149, v150, v151
	v_cvt_pk_bf16_f32 v150, v144, v145
	v_cvt_pk_bf16_f32 v151, v146, v147
	v_permlane16_swap_b32_e32 v156, v158
	v_permlane16_swap_b32_e32 v157, v159
	v_permlane16_swap_b32_e32 v148, v150
	v_permlane16_swap_b32_e32 v149, v151
	global_store_dwordx4 v160, v[156:159], s[100:101] sc1
	global_store_dwordx4 v160, v[148:151], s[100:101] offset:64 sc1
	s_add_u32 s100, s100, 0x8000
	s_addc_u32 s101, s101, 0
	v_cvt_pk_bf16_f32 v140, v140, v141
	v_cvt_pk_bf16_f32 v141, v142, v143
	v_cvt_pk_bf16_f32 v142, v136, v137
	v_cvt_pk_bf16_f32 v143, v138, v139
	v_cvt_pk_bf16_f32 v132, v132, v133
	v_cvt_pk_bf16_f32 v133, v134, v135
	v_cvt_pk_bf16_f32 v134, v128, v129
	v_cvt_pk_bf16_f32 v135, v130, v131
	v_permlane16_swap_b32_e32 v140, v142
	v_permlane16_swap_b32_e32 v141, v143
	v_permlane16_swap_b32_e32 v132, v134
	v_permlane16_swap_b32_e32 v133, v135
	global_store_dwordx4 v160, v[140:143], s[100:101] sc1
	global_store_dwordx4 v160, v[132:135], s[100:101] offset:64 sc1
	s_add_u32 s100, s100, 0x8000
	s_addc_u32 s101, s101, 0
	v_cvt_pk_bf16_f32 v124, v124, v125
	v_cvt_pk_bf16_f32 v125, v126, v127
	v_cvt_pk_bf16_f32 v126, v120, v121
	v_cvt_pk_bf16_f32 v127, v122, v123
	v_cvt_pk_bf16_f32 v116, v116, v117
	v_cvt_pk_bf16_f32 v117, v118, v119
	v_cvt_pk_bf16_f32 v118, v112, v113
	v_cvt_pk_bf16_f32 v119, v114, v115
	v_permlane16_swap_b32_e32 v124, v126
	v_permlane16_swap_b32_e32 v125, v127
	v_permlane16_swap_b32_e32 v116, v118
	v_permlane16_swap_b32_e32 v117, v119
	global_store_dwordx4 v160, v[124:127], s[100:101] sc1
	global_store_dwordx4 v160, v[116:119], s[100:101] offset:64 sc1
	s_add_u32 s100, s100, 0x8000
	s_addc_u32 s101, s101, 0
	v_cvt_pk_bf16_f32 v108, v108, v109
	v_cvt_pk_bf16_f32 v109, v110, v111
	v_cvt_pk_bf16_f32 v110, v104, v105
	v_cvt_pk_bf16_f32 v111, v106, v107
	v_cvt_pk_bf16_f32 v100, v100, v101
	v_cvt_pk_bf16_f32 v101, v102, v103
	v_cvt_pk_bf16_f32 v102, v96, v97
	v_cvt_pk_bf16_f32 v103, v98, v99
	v_permlane16_swap_b32_e32 v108, v110
	v_permlane16_swap_b32_e32 v109, v111
	v_permlane16_swap_b32_e32 v100, v102
	v_permlane16_swap_b32_e32 v101, v103
	global_store_dwordx4 v160, v[108:111], s[100:101] sc1
	global_store_dwordx4 v160, v[100:103], s[100:101] offset:64 sc1
	s_add_u32 s100, s100, 0x8000
	s_addc_u32 s101, s101, 0
	v_cvt_pk_bf16_f32 v92, v92, v93
	v_cvt_pk_bf16_f32 v93, v94, v95
	v_cvt_pk_bf16_f32 v94, v88, v89
	v_cvt_pk_bf16_f32 v95, v90, v91
	v_cvt_pk_bf16_f32 v80, v80, v81
	v_cvt_pk_bf16_f32 v81, v82, v83
	v_cvt_pk_bf16_f32 v82, v84, v85
	v_cvt_pk_bf16_f32 v83, v86, v87
	v_permlane16_swap_b32_e32 v92, v94
	v_permlane16_swap_b32_e32 v93, v95
	v_permlane16_swap_b32_e32 v80, v82
	v_permlane16_swap_b32_e32 v81, v83
	global_store_dwordx4 v160, v[92:95], s[100:101] sc1
	global_store_dwordx4 v160, v[80:83], s[100:101] offset:64 sc1
	s_add_u32 s100, s100, 0x8000
	s_addc_u32 s101, s101, 0
	v_cvt_pk_bf16_f32 v76, v76, v77
	v_cvt_pk_bf16_f32 v77, v78, v79
	v_cvt_pk_bf16_f32 v78, v72, v73
	v_cvt_pk_bf16_f32 v79, v74, v75
	v_cvt_pk_bf16_f32 v68, v68, v69
	v_cvt_pk_bf16_f32 v69, v70, v71
	v_cvt_pk_bf16_f32 v70, v64, v65
	v_cvt_pk_bf16_f32 v71, v66, v67
	v_permlane16_swap_b32_e32 v76, v78
	v_permlane16_swap_b32_e32 v77, v79
	v_permlane16_swap_b32_e32 v68, v70
	v_permlane16_swap_b32_e32 v69, v71
	global_store_dwordx4 v160, v[76:79], s[100:101] sc1
	global_store_dwordx4 v160, v[68:71], s[100:101] offset:64 sc1
	s_add_u32 s100, s100, 0x8000
	s_addc_u32 s101, s101, 0
	v_cvt_pk_bf16_f32 v60, v60, v61
	v_cvt_pk_bf16_f32 v61, v62, v63
	v_cvt_pk_bf16_f32 v62, v56, v57
	v_cvt_pk_bf16_f32 v63, v58, v59
	v_cvt_pk_bf16_f32 v52, v52, v53
	v_cvt_pk_bf16_f32 v53, v54, v55
	v_cvt_pk_bf16_f32 v54, v48, v49
	v_cvt_pk_bf16_f32 v55, v50, v51
	v_permlane16_swap_b32_e32 v60, v62
	v_permlane16_swap_b32_e32 v61, v63
	v_permlane16_swap_b32_e32 v52, v54
	v_permlane16_swap_b32_e32 v53, v55
	global_store_dwordx4 v160, v[60:63], s[100:101] sc1
	global_store_dwordx4 v160, v[52:55], s[100:101] offset:64 sc1
	s_add_u32 s100, s100, 0x8000
	s_addc_u32 s101, s101, 0
	v_cvt_pk_bf16_f32 v40, v40, v41
	v_cvt_pk_bf16_f32 v41, v42, v43
	v_cvt_pk_bf16_f32 v42, v36, v37
	v_cvt_pk_bf16_f32 v43, v38, v39
	v_cvt_pk_bf16_f32 v32, v32, v33
	v_cvt_pk_bf16_f32 v33, v34, v35
	v_cvt_pk_bf16_f32 v34, v44, v45
	v_cvt_pk_bf16_f32 v35, v46, v47
	v_permlane16_swap_b32_e32 v40, v42
	v_permlane16_swap_b32_e32 v41, v43
	v_permlane16_swap_b32_e32 v32, v34
	v_permlane16_swap_b32_e32 v33, v35
	global_store_dwordx4 v160, v[40:43], s[100:101] sc1
	global_store_dwordx4 v160, v[32:35], s[100:101] offset:64 sc1
	s_and_b64 vcc, exec, s[50:51]
	s_mov_b32 s56, s48
	s_mov_b32 s75, s74
	s_mov_b32 s76, s73
	s_mov_b64 s[60:61], s[44:45]
	s_mov_b64 s[58:59], s[42:43]
	s_cbranch_vccz .LBB0_1017
	s_load_dwordx16 s[36:51], s[0:1], 0xc0

.LBB0_1146:
	ds_read_b128 v[160:163], v196
	ds_read_b128 v[164:167], v197
	ds_read_b128 v[180:183], v197 offset:64
	ds_read_b128 v[168:171], v196 offset:64
	ds_read_b128 v[172:175], v197 offset:2304
	ds_read_b128 v[206:209], v197 offset:2368
	ds_read_b128 v[176:179], v197 offset:4608
	ds_read_b128 v[210:213], v197 offset:4672
	ds_read_b128 v[184:187], v197 offset:6912
	ds_read_b128 v[214:217], v197 offset:6976
	s_waitcnt lgkmcnt(8)
	v_mfma_f32_16x16x32_bf16 v[156:159], v[164:167], v[160:163], v[156:159]
	s_add_i32 s41, s41, 2
	s_add_u32 s42, s39, 0xffffff80
	s_addc_u32 s43, s40, -1
	s_waitcnt lgkmcnt(5)
	v_mfma_f32_16x16x32_bf16 v[152:155], v[172:175], v[160:163], v[152:155]
	s_add_u32 s44, s26, 0xffffff80
	s_addc_u32 s45, s27, -1
	s_cmp_gt_u32 s41, 13
	s_waitcnt lgkmcnt(3)
	v_mfma_f32_16x16x32_bf16 v[148:151], v[176:179], v[160:163], v[148:151]
	s_cselect_b64 s[4:5], -1, 0
	s_and_b64 vcc, s[4:5], exec
	s_cselect_b32 s5, s11, s43
	s_waitcnt lgkmcnt(1)
	v_mfma_f32_16x16x32_bf16 v[144:147], v[184:187], v[160:163], v[144:147]
	ds_read_b128 v[160:163], v196 offset:2304
	ds_read_b128 v[188:191], v196 offset:2368
	s_cselect_b32 s4, s10, s42
	s_cselect_b32 s43, s13, s45
	s_waitcnt lgkmcnt(1)
	v_mfma_f32_16x16x32_bf16 v[140:143], v[164:167], v[160:163], v[140:143]
	s_cselect_b32 s42, s12, s44
	s_cmp_gt_u32 s41, 12
	v_mfma_f32_16x16x32_bf16 v[136:139], v[172:175], v[160:163], v[136:139]
	v_mfma_f32_16x16x32_bf16 v[132:135], v[176:179], v[160:163], v[132:135]
	v_mfma_f32_16x16x32_bf16 v[128:131], v[184:187], v[160:163], v[128:131]
	ds_read_b128 v[160:163], v196 offset:4608
	ds_read_b128 v[218:221], v196 offset:4672
	s_waitcnt lgkmcnt(1)
	v_mfma_f32_16x16x32_bf16 v[124:127], v[164:167], v[160:163], v[124:127]
	v_mfma_f32_16x16x32_bf16 v[120:123], v[172:175], v[160:163], v[120:123]
	v_mfma_f32_16x16x32_bf16 v[116:119], v[176:179], v[160:163], v[116:119]
	v_mfma_f32_16x16x32_bf16 v[112:115], v[184:187], v[160:163], v[112:115]
	ds_read_b128 v[160:163], v196 offset:6912
	ds_read_b128 v[222:225], v196 offset:6976
	s_waitcnt lgkmcnt(1)
	v_mfma_f32_16x16x32_bf16 v[108:111], v[164:167], v[160:163], v[108:111]
	v_mfma_f32_16x16x32_bf16 v[104:107], v[172:175], v[160:163], v[104:107]
	v_mfma_f32_16x16x32_bf16 v[100:103], v[176:179], v[160:163], v[100:103]
	v_mfma_f32_16x16x32_bf16 v[96:99], v[184:187], v[160:163], v[96:99]
	ds_read_b128 v[160:163], v196 offset:9216
	ds_read_b128 v[226:229], v196 offset:9280
	s_waitcnt lgkmcnt(1)
	v_mfma_f32_16x16x32_bf16 v[92:95], v[164:167], v[160:163], v[92:95]
	v_mfma_f32_16x16x32_bf16 v[88:91], v[172:175], v[160:163], v[88:91]
	v_mfma_f32_16x16x32_bf16 v[84:87], v[176:179], v[160:163], v[84:87]
	v_mfma_f32_16x16x32_bf16 v[80:83], v[184:187], v[160:163], v[80:83]
	ds_read_b128 v[160:163], v196 offset:11520
	ds_read_b128 v[230:233], v196 offset:11584
	s_waitcnt lgkmcnt(1)
	v_mfma_f32_16x16x32_bf16 v[76:79], v[164:167], v[160:163], v[76:79]
	v_mfma_f32_16x16x32_bf16 v[72:75], v[172:175], v[160:163], v[72:75]
	v_mfma_f32_16x16x32_bf16 v[68:71], v[176:179], v[160:163], v[68:71]
	v_mfma_f32_16x16x32_bf16 v[64:67], v[184:187], v[160:163], v[64:67]
	ds_read_b128 v[160:163], v196 offset:13824
	ds_read_b128 v[234:237], v196 offset:13888
	s_waitcnt lgkmcnt(1)
	v_mfma_f32_16x16x32_bf16 v[60:63], v[164:167], v[160:163], v[60:63]
	v_mfma_f32_16x16x32_bf16 v[56:59], v[172:175], v[160:163], v[56:59]
	v_mfma_f32_16x16x32_bf16 v[52:55], v[176:179], v[160:163], v[52:55]
	v_mfma_f32_16x16x32_bf16 v[48:51], v[184:187], v[160:163], v[48:51]
	ds_read_b128 v[160:163], v196 offset:16128
	ds_read_b128 v[238:241], v196 offset:16192
	s_waitcnt vmcnt(6)
	ds_write_b128 v194, v[4:7] offset:36864
	s_waitcnt vmcnt(5)
	ds_write_b128 v194, v[8:11] offset:46080
	s_waitcnt vmcnt(4)
	ds_write_b128 v194, v[12:15] offset:55296
	s_waitcnt vmcnt(3)
	ds_write_b128 v194, v[16:19] offset:64512
	s_waitcnt vmcnt(3)
	ds_write_b128 v199, v[0:3]
	s_waitcnt vmcnt(2)
	ds_write_b128 v199, v[20:23] offset:9216
	v_mfma_f32_16x16x32_bf16 v[20:23], v[214:217], v[226:229], v[80:83]
	s_waitcnt vmcnt(1)
	ds_write_b128 v199, v[24:27] offset:18432
	s_waitcnt vmcnt(0)
	ds_write_b128 v199, v[28:31] offset:27648
	v_lshl_add_u64 v[80:81], s[4:5], 0, v[192:193]
	v_mfma_f32_16x16x32_bf16 v[24:27], v[180:183], v[230:233], v[76:79]
	v_lshl_add_u64 v[82:83], s[42:43], 0, v[192:193]
	s_cselect_b32 s43, s38, s27
	s_cselect_b32 s42, s37, s26
	v_add_co_u32_e64 v76, s[4:5], s23, v80
	v_mfma_f32_16x16x32_bf16 v[28:31], v[206:209], v[230:233], v[72:75]
	s_nop 0
	v_addc_co_u32_e64 v77, s[4:5], 0, v81, s[4:5]
	s_nop 0
	v_add_co_u32_e64 v72, s[4:5], s25, v80
	s_waitcnt lgkmcnt(9)
	v_mfma_f32_16x16x32_bf16 v[36:39], v[164:167], v[160:163], v[36:39]
	v_addc_co_u32_e64 v73, s[4:5], 0, v81, s[4:5]
	v_add_co_u32_e64 v74, s[4:5], s30, v80
	v_mfma_f32_16x16x32_bf16 v[32:35], v[172:175], v[160:163], v[32:35]
	s_nop 0
	v_addc_co_u32_e64 v75, s[4:5], 0, v81, s[4:5]
	v_add_co_u32_e64 v78, s[4:5], s23, v82
	v_mfma_f32_16x16x32_bf16 v[44:47], v[176:179], v[160:163], v[44:47]
	s_nop 0
	v_addc_co_u32_e64 v79, s[4:5], 0, v83, s[4:5]
	global_load_dwordx4 v[164:167], v[82:83], off
	v_mfma_f32_16x16x32_bf16 v[40:43], v[184:187], v[160:163], v[40:43]
	global_load_dwordx4 v[160:163], v[80:81], off
	v_add_co_u32_e64 v80, s[4:5], s25, v82
	v_mfma_f32_16x16x32_bf16 v[156:159], v[180:183], v[168:171], v[156:159]
	s_nop 0
	v_addc_co_u32_e64 v81, s[4:5], 0, v83, s[4:5]
	v_add_co_u32_e64 v82, s[4:5], s30, v82
	v_mfma_f32_16x16x32_bf16 v[152:155], v[206:209], v[168:171], v[152:155]
	s_nop 0
	v_addc_co_u32_e64 v83, s[4:5], 0, v83, s[4:5]
	s_cselect_b32 s5, s21, s40
	v_mfma_f32_16x16x32_bf16 v[148:151], v[210:213], v[168:171], v[148:151]
	s_cselect_b32 s4, s19, s39
	s_add_u32 s26, s26, 0x100
	s_addc_u32 s27, s27, 0
	v_mfma_f32_16x16x32_bf16 v[144:147], v[214:217], v[168:171], v[144:147]
	global_load_dwordx4 v[168:171], v[76:77], off
	global_load_dwordx4 v[172:175], v[72:73], off
	global_load_dwordx4 v[176:179], v[74:75], off
	s_add_u32 s39, s39, 0x100
	s_addc_u32 s40, s40, 0
	v_mfma_f32_16x16x32_bf16 v[140:143], v[180:183], v[188:191], v[140:143]
	v_mfma_f32_16x16x32_bf16 v[136:139], v[206:209], v[188:191], v[136:139]
	v_mfma_f32_16x16x32_bf16 v[132:135], v[210:213], v[188:191], v[132:135]
	v_mfma_f32_16x16x32_bf16 v[128:131], v[214:217], v[188:191], v[128:131]
	v_mfma_f32_16x16x32_bf16 v[124:127], v[180:183], v[218:221], v[124:127]
	v_mfma_f32_16x16x32_bf16 v[108:111], v[180:183], v[222:225], v[108:111]
	v_mfma_f32_16x16x32_bf16 v[8:11], v[180:183], v[226:229], v[92:95]
	v_mfma_f32_16x16x32_bf16 v[60:63], v[180:183], v[234:237], v[60:63]
	s_waitcnt lgkmcnt(8)
	v_mfma_f32_16x16x32_bf16 v[36:39], v[180:183], v[238:241], v[36:39]
	global_load_dwordx4 v[180:183], v[78:79], off
	global_load_dwordx4 v[184:187], v[80:81], off
	global_load_dwordx4 v[188:191], v[82:83], off
	s_waitcnt lgkmcnt(0)
	s_barrier
	ds_read_b128 v[76:79], v196 offset:36864
	v_mfma_f32_16x16x32_bf16 v[120:123], v[206:209], v[218:221], v[120:123]
	v_mfma_f32_16x16x32_bf16 v[116:119], v[210:213], v[218:221], v[116:119]
	v_mfma_f32_16x16x32_bf16 v[104:107], v[206:209], v[222:225], v[104:107]
	v_mfma_f32_16x16x32_bf16 v[4:7], v[210:213], v[222:225], v[100:103]
	v_mfma_f32_16x16x32_bf16 v[0:3], v[214:217], v[222:225], v[96:99]
	v_mfma_f32_16x16x32_bf16 v[12:15], v[206:209], v[226:229], v[88:91]
	v_mfma_f32_16x16x32_bf16 v[16:19], v[210:213], v[226:229], v[84:87]
	v_mfma_f32_16x16x32_bf16 v[68:71], v[210:213], v[230:233], v[68:71]
	v_mfma_f32_16x16x32_bf16 v[56:59], v[206:209], v[234:237], v[56:59]
	v_mfma_f32_16x16x32_bf16 v[52:55], v[210:213], v[234:237], v[52:55]
	v_mfma_f32_16x16x32_bf16 v[32:35], v[206:209], v[238:241], v[32:35]
	ds_read_b128 v[84:87], v200
	ds_read_b128 v[206:209], v200 offset:64
	ds_read_b128 v[88:91], v196 offset:36928
	v_mfma_f32_16x16x32_bf16 v[72:75], v[210:213], v[238:241], v[44:47]
	ds_read_b128 v[96:99], v200 offset:2304
	ds_read_b128 v[210:213], v200 offset:2368
	v_mfma_f32_16x16x32_bf16 v[80:83], v[214:217], v[238:241], v[40:43]
	s_waitcnt lgkmcnt(4)
	v_mfma_f32_16x16x32_bf16 v[92:95], v[84:87], v[76:79], v[156:159]
	s_waitcnt lgkmcnt(1)
	v_mfma_f32_16x16x32_bf16 v[100:103], v[96:99], v[76:79], v[152:155]
	s_nop 2
	ds_read_b128 v[152:155], v200 offset:4608
	ds_read_b128 v[44:47], v200 offset:4672
	ds_read_b128 v[156:159], v200 offset:6912
	ds_read_b128 v[40:43], v200 offset:6976
	v_mfma_f32_16x16x32_bf16 v[112:115], v[214:217], v[218:221], v[112:115]
	v_mfma_f32_16x16x32_bf16 v[64:67], v[214:217], v[230:233], v[64:67]
	v_mfma_f32_16x16x32_bf16 v[48:51], v[214:217], v[234:237], v[48:51]
	s_waitcnt lgkmcnt(3)
	v_mfma_f32_16x16x32_bf16 v[148:151], v[152:155], v[76:79], v[148:151]
	s_waitcnt lgkmcnt(1)
	v_mfma_f32_16x16x32_bf16 v[76:79], v[156:159], v[76:79], v[144:147]
	s_nop 2
	ds_read_b128 v[144:147], v196 offset:39168
	ds_read_b128 v[214:217], v196 offset:39232
	s_waitcnt lgkmcnt(1)
	v_mfma_f32_16x16x32_bf16 v[140:143], v[84:87], v[144:147], v[140:143]
	v_mfma_f32_16x16x32_bf16 v[136:139], v[96:99], v[144:147], v[136:139]
	v_mfma_f32_16x16x32_bf16 v[132:135], v[152:155], v[144:147], v[132:135]
	v_mfma_f32_16x16x32_bf16 v[128:131], v[156:159], v[144:147], v[128:131]
	ds_read_b128 v[144:147], v196 offset:41472
	ds_read_b128 v[218:221], v196 offset:41536
	s_waitcnt lgkmcnt(1)
	v_mfma_f32_16x16x32_bf16 v[124:127], v[84:87], v[144:147], v[124:127]
	v_mfma_f32_16x16x32_bf16 v[120:123], v[96:99], v[144:147], v[120:123]
	v_mfma_f32_16x16x32_bf16 v[116:119], v[152:155], v[144:147], v[116:119]
	v_mfma_f32_16x16x32_bf16 v[112:115], v[156:159], v[144:147], v[112:115]
	ds_read_b128 v[144:147], v196 offset:43776
	ds_read_b128 v[222:225], v196 offset:43840
	s_waitcnt lgkmcnt(1)
	v_mfma_f32_16x16x32_bf16 v[108:111], v[84:87], v[144:147], v[108:111]
	v_mfma_f32_16x16x32_bf16 v[104:107], v[96:99], v[144:147], v[104:107]
	v_mfma_f32_16x16x32_bf16 v[4:7], v[152:155], v[144:147], v[4:7]
	v_mfma_f32_16x16x32_bf16 v[0:3], v[156:159], v[144:147], v[0:3]
	ds_read_b128 v[144:147], v196 offset:46080
	ds_read_b128 v[226:229], v196 offset:46144
	s_waitcnt lgkmcnt(1)
	v_mfma_f32_16x16x32_bf16 v[8:11], v[84:87], v[144:147], v[8:11]
	v_mfma_f32_16x16x32_bf16 v[12:15], v[96:99], v[144:147], v[12:15]
	v_mfma_f32_16x16x32_bf16 v[16:19], v[152:155], v[144:147], v[16:19]
	v_mfma_f32_16x16x32_bf16 v[20:23], v[156:159], v[144:147], v[20:23]
	ds_read_b128 v[144:147], v196 offset:48384
	ds_read_b128 v[230:233], v196 offset:48448
	s_waitcnt lgkmcnt(1)
	v_mfma_f32_16x16x32_bf16 v[24:27], v[84:87], v[144:147], v[24:27]
	v_mfma_f32_16x16x32_bf16 v[28:31], v[96:99], v[144:147], v[28:31]
	v_mfma_f32_16x16x32_bf16 v[68:71], v[152:155], v[144:147], v[68:71]
	v_mfma_f32_16x16x32_bf16 v[64:67], v[156:159], v[144:147], v[64:67]
	ds_read_b128 v[144:147], v196 offset:50688
	ds_read_b128 v[234:237], v196 offset:50752
	s_waitcnt lgkmcnt(1)
	v_mfma_f32_16x16x32_bf16 v[60:63], v[84:87], v[144:147], v[60:63]
	v_mfma_f32_16x16x32_bf16 v[56:59], v[96:99], v[144:147], v[56:59]
	v_mfma_f32_16x16x32_bf16 v[52:55], v[152:155], v[144:147], v[52:55]
	v_mfma_f32_16x16x32_bf16 v[48:51], v[156:159], v[144:147], v[48:51]
	ds_read_b128 v[144:147], v196 offset:52992
	ds_read_b128 v[238:241], v196 offset:53056
	s_waitcnt lgkmcnt(1)
	v_mfma_f32_16x16x32_bf16 v[242:245], v[152:155], v[144:147], v[72:75]
	v_mfma_f32_16x16x32_bf16 v[152:155], v[210:213], v[88:91], v[100:103]
	v_mfma_f32_16x16x32_bf16 v[100:103], v[44:47], v[222:225], v[4:7]
	s_nop 2
	v_lshl_add_u64 v[4:5], s[4:5], 0, v[192:193]
	v_mfma_f32_16x16x32_bf16 v[246:249], v[156:159], v[144:147], v[80:83]
	v_lshl_add_u64 v[6:7], s[42:43], 0, v[192:193]
	v_mfma_f32_16x16x32_bf16 v[156:159], v[206:209], v[88:91], v[92:95]
	v_mfma_f32_16x16x32_bf16 v[92:95], v[206:209], v[226:229], v[8:11]
	s_nop 2
	v_add_co_u32_e64 v8, s[4:5], s23, v4
	v_mfma_f32_16x16x32_bf16 v[36:39], v[84:87], v[144:147], v[36:39]
	s_nop 0
	v_addc_co_u32_e64 v9, s[4:5], 0, v5, s[4:5]
	v_mfma_f32_16x16x32_bf16 v[32:35], v[96:99], v[144:147], v[32:35]
	v_mfma_f32_16x16x32_bf16 v[148:151], v[44:47], v[88:91], v[148:151]
	v_mfma_f32_16x16x32_bf16 v[144:147], v[40:43], v[88:91], v[76:79]
	v_mfma_f32_16x16x32_bf16 v[88:91], v[210:213], v[226:229], v[12:15]
	s_nop 2
	v_add_co_u32_e64 v12, s[4:5], s25, v4
	v_mfma_f32_16x16x32_bf16 v[84:87], v[44:47], v[226:229], v[16:19]
	s_nop 0
	v_addc_co_u32_e64 v13, s[4:5], 0, v5, s[4:5]
	s_nop 0
	v_add_co_u32_e64 v16, s[4:5], s30, v4
	v_mfma_f32_16x16x32_bf16 v[80:83], v[40:43], v[226:229], v[20:23]
	s_nop 0
	v_addc_co_u32_e64 v17, s[4:5], 0, v5, s[4:5]
	s_nop 0
	v_add_co_u32_e64 v20, s[4:5], s23, v6
	v_mfma_f32_16x16x32_bf16 v[76:79], v[206:209], v[230:233], v[24:27]
	s_nop 0
	v_addc_co_u32_e64 v21, s[4:5], 0, v7, s[4:5]
	s_nop 0
	v_add_co_u32_e64 v24, s[4:5], s25, v6
	v_mfma_f32_16x16x32_bf16 v[72:75], v[210:213], v[230:233], v[28:31]
	s_nop 0
	v_addc_co_u32_e64 v25, s[4:5], 0, v7, s[4:5]
	s_nop 0
	v_add_co_u32_e64 v28, s[4:5], s30, v6
	v_mfma_f32_16x16x32_bf16 v[96:99], v[40:43], v[222:225], v[0:3]
	s_nop 0
	v_addc_co_u32_e64 v29, s[4:5], 0, v7, s[4:5]
	s_nop 0
	global_load_dwordx4 v[0:3], v[6:7], off
	s_nop 0
	global_load_dwordx4 v[4:7], v[4:5], off
	s_nop 0
	global_load_dwordx4 v[8:11], v[8:9], off
	s_nop 0
	global_load_dwordx4 v[12:15], v[12:13], off
	s_nop 0
	global_load_dwordx4 v[16:19], v[16:17], off
	s_nop 0
	global_load_dwordx4 v[20:23], v[20:21], off
	s_nop 0
	global_load_dwordx4 v[24:27], v[24:25], off
	v_mfma_f32_16x16x32_bf16 v[140:143], v[206:209], v[214:217], v[140:143]
	global_load_dwordx4 v[28:31], v[28:29], off
	s_waitcnt vmcnt(14)
	ds_write_b128 v194, v[160:163]
	ds_write_b128 v195, v[164:167]
	s_waitcnt vmcnt(13)
	ds_write_b128 v194, v[168:171] offset:9216
	s_waitcnt vmcnt(12)
	ds_write_b128 v194, v[172:175] offset:18432
	s_waitcnt vmcnt(11)
	ds_write_b128 v194, v[176:179] offset:27648
	s_waitcnt vmcnt(10)
	ds_write_b128 v195, v[180:183] offset:9216
	s_waitcnt vmcnt(9)
	ds_write_b128 v195, v[184:187] offset:18432
	s_waitcnt vmcnt(8)
	ds_write_b128 v195, v[188:191] offset:27648
	s_waitcnt lgkmcnt(0)
	v_mfma_f32_16x16x32_bf16 v[136:139], v[210:213], v[214:217], v[136:139]
	s_barrier
	v_mfma_f32_16x16x32_bf16 v[132:135], v[44:47], v[214:217], v[132:135]
	v_mfma_f32_16x16x32_bf16 v[128:131], v[40:43], v[214:217], v[128:131]
	v_mfma_f32_16x16x32_bf16 v[124:127], v[206:209], v[218:221], v[124:127]
	v_mfma_f32_16x16x32_bf16 v[120:123], v[210:213], v[218:221], v[120:123]
	v_mfma_f32_16x16x32_bf16 v[116:119], v[44:47], v[218:221], v[116:119]
	v_mfma_f32_16x16x32_bf16 v[112:115], v[40:43], v[218:221], v[112:115]
	v_mfma_f32_16x16x32_bf16 v[108:111], v[206:209], v[222:225], v[108:111]
	v_mfma_f32_16x16x32_bf16 v[104:107], v[210:213], v[222:225], v[104:107]
	v_mfma_f32_16x16x32_bf16 v[68:71], v[44:47], v[230:233], v[68:71]
	v_mfma_f32_16x16x32_bf16 v[64:67], v[40:43], v[230:233], v[64:67]
	v_mfma_f32_16x16x32_bf16 v[60:63], v[206:209], v[234:237], v[60:63]
	v_mfma_f32_16x16x32_bf16 v[56:59], v[210:213], v[234:237], v[56:59]
	v_mfma_f32_16x16x32_bf16 v[52:55], v[44:47], v[234:237], v[52:55]
	v_mfma_f32_16x16x32_bf16 v[48:51], v[40:43], v[234:237], v[48:51]
	v_mfma_f32_16x16x32_bf16 v[36:39], v[206:209], v[238:241], v[36:39]
	v_mfma_f32_16x16x32_bf16 v[32:35], v[210:213], v[238:241], v[32:35]
	v_mfma_f32_16x16x32_bf16 v[44:47], v[44:47], v[238:241], v[242:245]
	v_mfma_f32_16x16x32_bf16 v[40:43], v[40:43], v[238:241], v[246:249]
	s_cbranch_vccz .LBB0_1146
	s_mul_i32 s98, s22, 0x1600
	s_add_u32 s98, s98, s24
	s_add_u32 s100, s8, s98
	s_addc_u32 s101, s9, 0
	v_and_b32_e32 v168, 15, v198
	v_and_b32_e32 v169, 0x80, v201
	v_add_u32_e32 v168, v168, v169
	v_mul_u32_u24_e32 v168, 0x1600, v168
	v_and_b32_e32 v169, 0xc0, v198
	v_add_u32_e32 v168, v168, v169
	v_and_b32_e32 v169, 4, v201
	v_lshl_add_u32 v168, v169, 3, v168
	v_and_b32_e32 v169, 8, v201
	v_lshl_add_u32 v168, v169, 1, v168
	v_mul_f32_e32 v160, 0xbfb8aa3b, v156
	v_mul_f32_e32 v161, 0xbfb8aa3b, v157
	v_mul_f32_e32 v162, 0xbfb8aa3b, v158
	v_mul_f32_e32 v163, 0xbfb8aa3b, v159
	v_mul_f32_e32 v164, 0xbfb8aa3b, v148
	v_mul_f32_e32 v165, 0xbfb8aa3b, v149
	v_mul_f32_e32 v166, 0xbfb8aa3b, v150
	v_mul_f32_e32 v167, 0xbfb8aa3b, v151
	v_exp_f32_e32 v160, v160
	v_exp_f32_e32 v161, v161
	v_exp_f32_e32 v162, v162
	v_exp_f32_e32 v163, v163
	v_exp_f32_e32 v164, v164
	v_exp_f32_e32 v165, v165
	v_exp_f32_e32 v166, v166
	v_exp_f32_e32 v167, v167
	v_add_f32_e32 v160, 1.0, v160
	v_add_f32_e32 v161, 1.0, v161
	v_add_f32_e32 v162, 1.0, v162
	v_add_f32_e32 v163, 1.0, v163
	v_add_f32_e32 v164, 1.0, v164
	v_add_f32_e32 v165, 1.0, v165
	v_add_f32_e32 v166, 1.0, v166
	v_add_f32_e32 v167, 1.0, v167
	v_rcp_f32_e32 v160, v160
	v_rcp_f32_e32 v161, v161
	v_rcp_f32_e32 v162, v162
	v_rcp_f32_e32 v163, v163
	v_rcp_f32_e32 v164, v164
	v_rcp_f32_e32 v165, v165
	v_rcp_f32_e32 v166, v166
	v_rcp_f32_e32 v167, v167
	v_mul_f32_e32 v156, v156, v160
	v_mul_f32_e32 v157, v157, v161
	v_mul_f32_e32 v158, v158, v162
	v_mul_f32_e32 v159, v159, v163
	v_mul_f32_e32 v148, v148, v164
	v_mul_f32_e32 v149, v149, v165
	v_mul_f32_e32 v150, v150, v166
	v_mul_f32_e32 v151, v151, v167
	v_mul_f32_e32 v152, v156, v152
	v_mul_f32_e32 v153, v157, v153
	v_mul_f32_e32 v154, v158, v154
	v_mul_f32_e32 v155, v159, v155
	v_mul_f32_e32 v144, v148, v144
	v_mul_f32_e32 v145, v149, v145
	v_mul_f32_e32 v146, v150, v146
	v_mul_f32_e32 v147, v151, v147
	v_cvt_pk_bf16_f32 v156, v152, v153
	v_cvt_pk_bf16_f32 v157, v154, v155
	v_cvt_pk_bf16_f32 v158, v144, v145
	v_cvt_pk_bf16_f32 v159, v146, v147
	s_nop 1
	v_permlane16_swap_b32_e32 v156, v158
	v_permlane16_swap_b32_e32 v157, v159
	global_store_dwordx4 v168, v[156:159], s[100:101] sc1
	s_add_u32 s100, s100, 0x16000
	s_addc_u32 s101, s101, 0
	v_mul_f32_e32 v160, 0xbfb8aa3b, v140
	v_mul_f32_e32 v161, 0xbfb8aa3b, v141
	v_mul_f32_e32 v162, 0xbfb8aa3b, v142
	v_mul_f32_e32 v163, 0xbfb8aa3b, v143
	v_mul_f32_e32 v164, 0xbfb8aa3b, v132
	v_mul_f32_e32 v165, 0xbfb8aa3b, v133
	v_mul_f32_e32 v166, 0xbfb8aa3b, v134
	v_mul_f32_e32 v167, 0xbfb8aa3b, v135
	v_exp_f32_e32 v160, v160
	v_exp_f32_e32 v161, v161
	v_exp_f32_e32 v162, v162
	v_exp_f32_e32 v163, v163
	v_exp_f32_e32 v164, v164
	v_exp_f32_e32 v165, v165
	v_exp_f32_e32 v166, v166
	v_exp_f32_e32 v167, v167
	v_add_f32_e32 v160, 1.0, v160
	v_add_f32_e32 v161, 1.0, v161
	v_add_f32_e32 v162, 1.0, v162
	v_add_f32_e32 v163, 1.0, v163
	v_add_f32_e32 v164, 1.0, v164
	v_add_f32_e32 v165, 1.0, v165
	v_add_f32_e32 v166, 1.0, v166
	v_add_f32_e32 v167, 1.0, v167
	v_rcp_f32_e32 v160, v160
	v_rcp_f32_e32 v161, v161
	v_rcp_f32_e32 v162, v162
	v_rcp_f32_e32 v163, v163
	v_rcp_f32_e32 v164, v164
	v_rcp_f32_e32 v165, v165
	v_rcp_f32_e32 v166, v166
	v_rcp_f32_e32 v167, v167
	v_mul_f32_e32 v140, v140, v160
	v_mul_f32_e32 v141, v141, v161
	v_mul_f32_e32 v142, v142, v162
	v_mul_f32_e32 v143, v143, v163
	v_mul_f32_e32 v132, v132, v164
	v_mul_f32_e32 v133, v133, v165
	v_mul_f32_e32 v134, v134, v166
	v_mul_f32_e32 v135, v135, v167
	v_mul_f32_e32 v136, v140, v136
	v_mul_f32_e32 v137, v141, v137
	v_mul_f32_e32 v138, v142, v138
	v_mul_f32_e32 v139, v143, v139
	v_mul_f32_e32 v128, v132, v128
	v_mul_f32_e32 v129, v133, v129
	v_mul_f32_e32 v130, v134, v130
	v_mul_f32_e32 v131, v135, v131
	v_cvt_pk_bf16_f32 v140, v136, v137
	v_cvt_pk_bf16_f32 v141, v138, v139
	v_cvt_pk_bf16_f32 v142, v128, v129
	v_cvt_pk_bf16_f32 v143, v130, v131
	s_nop 1
	v_permlane16_swap_b32_e32 v140, v142
	v_permlane16_swap_b32_e32 v141, v143
	global_store_dwordx4 v168, v[140:143], s[100:101] sc1
	s_add_u32 s100, s100, 0x16000
	s_addc_u32 s101, s101, 0
	v_mul_f32_e32 v160, 0xbfb8aa3b, v124
	v_mul_f32_e32 v161, 0xbfb8aa3b, v125
	v_mul_f32_e32 v162, 0xbfb8aa3b, v126
	v_mul_f32_e32 v163, 0xbfb8aa3b, v127
	v_mul_f32_e32 v164, 0xbfb8aa3b, v116
	v_mul_f32_e32 v165, 0xbfb8aa3b, v117
	v_mul_f32_e32 v166, 0xbfb8aa3b, v118
	v_mul_f32_e32 v167, 0xbfb8aa3b, v119
	v_exp_f32_e32 v160, v160
	v_exp_f32_e32 v161, v161
	v_exp_f32_e32 v162, v162
	v_exp_f32_e32 v163, v163
	v_exp_f32_e32 v164, v164
	v_exp_f32_e32 v165, v165
	v_exp_f32_e32 v166, v166
	v_exp_f32_e32 v167, v167
	v_add_f32_e32 v160, 1.0, v160
	v_add_f32_e32 v161, 1.0, v161
	v_add_f32_e32 v162, 1.0, v162
	v_add_f32_e32 v163, 1.0, v163
	v_add_f32_e32 v164, 1.0, v164
	v_add_f32_e32 v165, 1.0, v165
	v_add_f32_e32 v166, 1.0, v166
	v_add_f32_e32 v167, 1.0, v167
	v_rcp_f32_e32 v160, v160
	v_rcp_f32_e32 v161, v161
	v_rcp_f32_e32 v162, v162
	v_rcp_f32_e32 v163, v163
	v_rcp_f32_e32 v164, v164
	v_rcp_f32_e32 v165, v165
	v_rcp_f32_e32 v166, v166
	v_rcp_f32_e32 v167, v167
	v_mul_f32_e32 v124, v124, v160
	v_mul_f32_e32 v125, v125, v161
	v_mul_f32_e32 v126, v126, v162
	v_mul_f32_e32 v127, v127, v163
	v_mul_f32_e32 v116, v116, v164
	v_mul_f32_e32 v117, v117, v165
	v_mul_f32_e32 v118, v118, v166
	v_mul_f32_e32 v119, v119, v167
	v_mul_f32_e32 v120, v124, v120
	v_mul_f32_e32 v121, v125, v121
	v_mul_f32_e32 v122, v126, v122
	v_mul_f32_e32 v123, v127, v123
	v_mul_f32_e32 v112, v116, v112
	v_mul_f32_e32 v113, v117, v113
	v_mul_f32_e32 v114, v118, v114
	v_mul_f32_e32 v115, v119, v115
	v_cvt_pk_bf16_f32 v124, v120, v121
	v_cvt_pk_bf16_f32 v125, v122, v123
	v_cvt_pk_bf16_f32 v126, v112, v113
	v_cvt_pk_bf16_f32 v127, v114, v115
	s_nop 1
	v_permlane16_swap_b32_e32 v124, v126
	v_permlane16_swap_b32_e32 v125, v127
	global_store_dwordx4 v168, v[124:127], s[100:101] sc1
	s_add_u32 s100, s100, 0x16000
	s_addc_u32 s101, s101, 0
	v_mul_f32_e32 v160, 0xbfb8aa3b, v108
	v_mul_f32_e32 v161, 0xbfb8aa3b, v109
	v_mul_f32_e32 v162, 0xbfb8aa3b, v110
	v_mul_f32_e32 v163, 0xbfb8aa3b, v111
	v_mul_f32_e32 v164, 0xbfb8aa3b, v100
	v_mul_f32_e32 v165, 0xbfb8aa3b, v101
	v_mul_f32_e32 v166, 0xbfb8aa3b, v102
	v_mul_f32_e32 v167, 0xbfb8aa3b, v103
	v_exp_f32_e32 v160, v160
	v_exp_f32_e32 v161, v161
	v_exp_f32_e32 v162, v162
	v_exp_f32_e32 v163, v163
	v_exp_f32_e32 v164, v164
	v_exp_f32_e32 v165, v165
	v_exp_f32_e32 v166, v166
	v_exp_f32_e32 v167, v167
	v_add_f32_e32 v160, 1.0, v160
	v_add_f32_e32 v161, 1.0, v161
	v_add_f32_e32 v162, 1.0, v162
	v_add_f32_e32 v163, 1.0, v163
	v_add_f32_e32 v164, 1.0, v164
	v_add_f32_e32 v165, 1.0, v165
	v_add_f32_e32 v166, 1.0, v166
	v_add_f32_e32 v167, 1.0, v167
	v_rcp_f32_e32 v160, v160
	v_rcp_f32_e32 v161, v161
	v_rcp_f32_e32 v162, v162
	v_rcp_f32_e32 v163, v163
	v_rcp_f32_e32 v164, v164
	v_rcp_f32_e32 v165, v165
	v_rcp_f32_e32 v166, v166
	v_rcp_f32_e32 v167, v167
	v_mul_f32_e32 v108, v108, v160
	v_mul_f32_e32 v109, v109, v161
	v_mul_f32_e32 v110, v110, v162
	v_mul_f32_e32 v111, v111, v163
	v_mul_f32_e32 v100, v100, v164
	v_mul_f32_e32 v101, v101, v165
	v_mul_f32_e32 v102, v102, v166
	v_mul_f32_e32 v103, v103, v167
	v_mul_f32_e32 v104, v108, v104
	v_mul_f32_e32 v105, v109, v105
	v_mul_f32_e32 v106, v110, v106
	v_mul_f32_e32 v107, v111, v107
	v_mul_f32_e32 v96, v100, v96
	v_mul_f32_e32 v97, v101, v97
	v_mul_f32_e32 v98, v102, v98
	v_mul_f32_e32 v99, v103, v99
	v_cvt_pk_bf16_f32 v108, v104, v105
	v_cvt_pk_bf16_f32 v109, v106, v107
	v_cvt_pk_bf16_f32 v110, v96, v97
	v_cvt_pk_bf16_f32 v111, v98, v99
	s_nop 1
	v_permlane16_swap_b32_e32 v108, v110
	v_permlane16_swap_b32_e32 v109, v111
	global_store_dwordx4 v168, v[108:111], s[100:101] sc1
	s_add_u32 s100, s100, 0x16000
	s_addc_u32 s101, s101, 0
	v_mul_f32_e32 v160, 0xbfb8aa3b, v92
	v_mul_f32_e32 v161, 0xbfb8aa3b, v93
	v_mul_f32_e32 v162, 0xbfb8aa3b, v94
	v_mul_f32_e32 v163, 0xbfb8aa3b, v95
	v_mul_f32_e32 v164, 0xbfb8aa3b, v84
	v_mul_f32_e32 v165, 0xbfb8aa3b, v85
	v_mul_f32_e32 v166, 0xbfb8aa3b, v86
	v_mul_f32_e32 v167, 0xbfb8aa3b, v87
	v_exp_f32_e32 v160, v160
	v_exp_f32_e32 v161, v161
	v_exp_f32_e32 v162, v162
	v_exp_f32_e32 v163, v163
	v_exp_f32_e32 v164, v164
	v_exp_f32_e32 v165, v165
	v_exp_f32_e32 v166, v166
	v_exp_f32_e32 v167, v167
	v_add_f32_e32 v160, 1.0, v160
	v_add_f32_e32 v161, 1.0, v161
	v_add_f32_e32 v162, 1.0, v162
	v_add_f32_e32 v163, 1.0, v163
	v_add_f32_e32 v164, 1.0, v164
	v_add_f32_e32 v165, 1.0, v165
	v_add_f32_e32 v166, 1.0, v166
	v_add_f32_e32 v167, 1.0, v167
	v_rcp_f32_e32 v160, v160
	v_rcp_f32_e32 v161, v161
	v_rcp_f32_e32 v162, v162
	v_rcp_f32_e32 v163, v163
	v_rcp_f32_e32 v164, v164
	v_rcp_f32_e32 v165, v165
	v_rcp_f32_e32 v166, v166
	v_rcp_f32_e32 v167, v167
	v_mul_f32_e32 v92, v92, v160
	v_mul_f32_e32 v93, v93, v161
	v_mul_f32_e32 v94, v94, v162
	v_mul_f32_e32 v95, v95, v163
	v_mul_f32_e32 v84, v84, v164
	v_mul_f32_e32 v85, v85, v165
	v_mul_f32_e32 v86, v86, v166
	v_mul_f32_e32 v87, v87, v167
	v_mul_f32_e32 v88, v92, v88
	v_mul_f32_e32 v89, v93, v89
	v_mul_f32_e32 v90, v94, v90
	v_mul_f32_e32 v91, v95, v91
	v_mul_f32_e32 v80, v84, v80
	v_mul_f32_e32 v81, v85, v81
	v_mul_f32_e32 v82, v86, v82
	v_mul_f32_e32 v83, v87, v83
	v_cvt_pk_bf16_f32 v92, v88, v89
	v_cvt_pk_bf16_f32 v93, v90, v91
	v_cvt_pk_bf16_f32 v94, v80, v81
	v_cvt_pk_bf16_f32 v95, v82, v83
	s_nop 1
	v_permlane16_swap_b32_e32 v92, v94
	v_permlane16_swap_b32_e32 v93, v95
	global_store_dwordx4 v168, v[92:95], s[100:101] sc1
	s_add_u32 s100, s100, 0x16000
	s_addc_u32 s101, s101, 0
	v_mul_f32_e32 v160, 0xbfb8aa3b, v76
	v_mul_f32_e32 v161, 0xbfb8aa3b, v77
	v_mul_f32_e32 v162, 0xbfb8aa3b, v78
	v_mul_f32_e32 v163, 0xbfb8aa3b, v79
	v_mul_f32_e32 v164, 0xbfb8aa3b, v68
	v_mul_f32_e32 v165, 0xbfb8aa3b, v69
	v_mul_f32_e32 v166, 0xbfb8aa3b, v70
	v_mul_f32_e32 v167, 0xbfb8aa3b, v71
	v_exp_f32_e32 v160, v160
	v_exp_f32_e32 v161, v161
	v_exp_f32_e32 v162, v162
	v_exp_f32_e32 v163, v163
	v_exp_f32_e32 v164, v164
	v_exp_f32_e32 v165, v165
	v_exp_f32_e32 v166, v166
	v_exp_f32_e32 v167, v167
	v_add_f32_e32 v160, 1.0, v160
	v_add_f32_e32 v161, 1.0, v161
	v_add_f32_e32 v162, 1.0, v162
	v_add_f32_e32 v163, 1.0, v163
	v_add_f32_e32 v164, 1.0, v164
	v_add_f32_e32 v165, 1.0, v165
	v_add_f32_e32 v166, 1.0, v166
	v_add_f32_e32 v167, 1.0, v167
	v_rcp_f32_e32 v160, v160
	v_rcp_f32_e32 v161, v161
	v_rcp_f32_e32 v162, v162
	v_rcp_f32_e32 v163, v163
	v_rcp_f32_e32 v164, v164
	v_rcp_f32_e32 v165, v165
	v_rcp_f32_e32 v166, v166
	v_rcp_f32_e32 v167, v167
	v_mul_f32_e32 v76, v76, v160
	v_mul_f32_e32 v77, v77, v161
	v_mul_f32_e32 v78, v78, v162
	v_mul_f32_e32 v79, v79, v163
	v_mul_f32_e32 v68, v68, v164
	v_mul_f32_e32 v69, v69, v165
	v_mul_f32_e32 v70, v70, v166
	v_mul_f32_e32 v71, v71, v167
	v_mul_f32_e32 v72, v76, v72
	v_mul_f32_e32 v73, v77, v73
	v_mul_f32_e32 v74, v78, v74
	v_mul_f32_e32 v75, v79, v75
	v_mul_f32_e32 v64, v68, v64
	v_mul_f32_e32 v65, v69, v65
	v_mul_f32_e32 v66, v70, v66
	v_mul_f32_e32 v67, v71, v67
	v_cvt_pk_bf16_f32 v76, v72, v73
	v_cvt_pk_bf16_f32 v77, v74, v75
	v_cvt_pk_bf16_f32 v78, v64, v65
	v_cvt_pk_bf16_f32 v79, v66, v67
	s_nop 1
	v_permlane16_swap_b32_e32 v76, v78
	v_permlane16_swap_b32_e32 v77, v79
	global_store_dwordx4 v168, v[76:79], s[100:101] sc1
	s_add_u32 s100, s100, 0x16000
	s_addc_u32 s101, s101, 0
	v_mul_f32_e32 v160, 0xbfb8aa3b, v60
	v_mul_f32_e32 v161, 0xbfb8aa3b, v61
	v_mul_f32_e32 v162, 0xbfb8aa3b, v62
	v_mul_f32_e32 v163, 0xbfb8aa3b, v63
	v_mul_f32_e32 v164, 0xbfb8aa3b, v52
	v_mul_f32_e32 v165, 0xbfb8aa3b, v53
	v_mul_f32_e32 v166, 0xbfb8aa3b, v54
	v_mul_f32_e32 v167, 0xbfb8aa3b, v55
	v_exp_f32_e32 v160, v160
	v_exp_f32_e32 v161, v161
	v_exp_f32_e32 v162, v162
	v_exp_f32_e32 v163, v163
	v_exp_f32_e32 v164, v164
	v_exp_f32_e32 v165, v165
	v_exp_f32_e32 v166, v166
	v_exp_f32_e32 v167, v167
	v_add_f32_e32 v160, 1.0, v160
	v_add_f32_e32 v161, 1.0, v161
	v_add_f32_e32 v162, 1.0, v162
	v_add_f32_e32 v163, 1.0, v163
	v_add_f32_e32 v164, 1.0, v164
	v_add_f32_e32 v165, 1.0, v165
	v_add_f32_e32 v166, 1.0, v166
	v_add_f32_e32 v167, 1.0, v167
	v_rcp_f32_e32 v160, v160
	v_rcp_f32_e32 v161, v161
	v_rcp_f32_e32 v162, v162
	v_rcp_f32_e32 v163, v163
	v_rcp_f32_e32 v164, v164
	v_rcp_f32_e32 v165, v165
	v_rcp_f32_e32 v166, v166
	v_rcp_f32_e32 v167, v167
	v_mul_f32_e32 v60, v60, v160
	v_mul_f32_e32 v61, v61, v161
	v_mul_f32_e32 v62, v62, v162
	v_mul_f32_e32 v63, v63, v163
	v_mul_f32_e32 v52, v52, v164
	v_mul_f32_e32 v53, v53, v165
	v_mul_f32_e32 v54, v54, v166
	v_mul_f32_e32 v55, v55, v167
	v_mul_f32_e32 v56, v60, v56
	v_mul_f32_e32 v57, v61, v57
	v_mul_f32_e32 v58, v62, v58
	v_mul_f32_e32 v59, v63, v59
	v_mul_f32_e32 v48, v52, v48
	v_mul_f32_e32 v49, v53, v49
	v_mul_f32_e32 v50, v54, v50
	v_mul_f32_e32 v51, v55, v51
	v_cvt_pk_bf16_f32 v60, v56, v57
	v_cvt_pk_bf16_f32 v61, v58, v59
	v_cvt_pk_bf16_f32 v62, v48, v49
	v_cvt_pk_bf16_f32 v63, v50, v51
	s_nop 1
	v_permlane16_swap_b32_e32 v60, v62
	v_permlane16_swap_b32_e32 v61, v63
	global_store_dwordx4 v168, v[60:63], s[100:101] sc1
	s_add_u32 s100, s100, 0x16000
	s_addc_u32 s101, s101, 0
	v_mul_f32_e32 v160, 0xbfb8aa3b, v36
	v_mul_f32_e32 v161, 0xbfb8aa3b, v37
	v_mul_f32_e32 v162, 0xbfb8aa3b, v38
	v_mul_f32_e32 v163, 0xbfb8aa3b, v39
	v_mul_f32_e32 v164, 0xbfb8aa3b, v44
	v_mul_f32_e32 v165, 0xbfb8aa3b, v45
	v_mul_f32_e32 v166, 0xbfb8aa3b, v46
	v_mul_f32_e32 v167, 0xbfb8aa3b, v47
	v_exp_f32_e32 v160, v160
	v_exp_f32_e32 v161, v161
	v_exp_f32_e32 v162, v162
	v_exp_f32_e32 v163, v163
	v_exp_f32_e32 v164, v164
	v_exp_f32_e32 v165, v165
	v_exp_f32_e32 v166, v166
	v_exp_f32_e32 v167, v167
	v_add_f32_e32 v160, 1.0, v160
	v_add_f32_e32 v161, 1.0, v161
	v_add_f32_e32 v162, 1.0, v162
	v_add_f32_e32 v163, 1.0, v163
	v_add_f32_e32 v164, 1.0, v164
	v_add_f32_e32 v165, 1.0, v165
	v_add_f32_e32 v166, 1.0, v166
	v_add_f32_e32 v167, 1.0, v167
	v_rcp_f32_e32 v160, v160
	v_rcp_f32_e32 v161, v161
	v_rcp_f32_e32 v162, v162
	v_rcp_f32_e32 v163, v163
	v_rcp_f32_e32 v164, v164
	v_rcp_f32_e32 v165, v165
	v_rcp_f32_e32 v166, v166
	v_rcp_f32_e32 v167, v167
	v_mul_f32_e32 v36, v36, v160
	v_mul_f32_e32 v37, v37, v161
	v_mul_f32_e32 v38, v38, v162
	v_mul_f32_e32 v39, v39, v163
	v_mul_f32_e32 v44, v44, v164
	v_mul_f32_e32 v45, v45, v165
	v_mul_f32_e32 v46, v46, v166
	v_mul_f32_e32 v47, v47, v167
	v_mul_f32_e32 v32, v36, v32
	v_mul_f32_e32 v33, v37, v33
	v_mul_f32_e32 v34, v38, v34
	v_mul_f32_e32 v35, v39, v35
	v_mul_f32_e32 v40, v44, v40
	v_mul_f32_e32 v41, v45, v41
	v_mul_f32_e32 v42, v46, v42
	v_mul_f32_e32 v43, v47, v43
	v_cvt_pk_bf16_f32 v36, v32, v33
	v_cvt_pk_bf16_f32 v37, v34, v35
	v_cvt_pk_bf16_f32 v38, v40, v41
	v_cvt_pk_bf16_f32 v39, v42, v43
	s_nop 1
	v_permlane16_swap_b32_e32 v36, v38
	v_permlane16_swap_b32_e32 v37, v39
	global_store_dwordx4 v168, v[36:39], s[100:101] sc1
	s_and_b64 vcc, exec, s[16:17]
	s_mov_b32 s24, s20
	s_mov_b32 s22, s18
	s_mov_b64 s[26:27], s[12:13]
	s_mov_b64 s[4:5], s[10:11]
	s_cbranch_vccz .LBB0_1143

.LBB0_1208:
	ds_read_b128 v[160:163], v200
	ds_read_b128 v[164:167], v201
	ds_read_b128 v[180:183], v201 offset:64
	ds_read_b128 v[168:171], v200 offset:64
	ds_read_b128 v[172:175], v201 offset:2304
	ds_read_b128 v[192:195], v201 offset:2368
	ds_read_b128 v[176:179], v201 offset:4608
	ds_read_b128 v[210:213], v201 offset:4672
	ds_read_b128 v[184:187], v201 offset:6912
	ds_read_b128 v[214:217], v201 offset:6976
	s_waitcnt lgkmcnt(8)
	v_mfma_f32_16x16x32_bf16 v[156:159], v[164:167], v[160:163], v[156:159]
	s_add_i32 s80, s79, 2
	s_add_u32 s81, s52, 0xffffff80
	s_addc_u32 s83, s53, -1
	s_waitcnt lgkmcnt(5)
	v_mfma_f32_16x16x32_bf16 v[152:155], v[172:175], v[160:163], v[152:155]
	s_add_u32 s84, s54, 0xffffff80
	s_addc_u32 s85, s55, -1
	s_cmp_lt_u32 s79, 20
	s_waitcnt lgkmcnt(3)
	v_mfma_f32_16x16x32_bf16 v[148:151], v[176:179], v[160:163], v[148:151]
	s_cselect_b32 s82, s81, s44
	s_cselect_b32 s83, s83, s45
	s_cselect_b32 s84, s84, s48
	s_waitcnt lgkmcnt(1)
	v_mfma_f32_16x16x32_bf16 v[144:147], v[184:187], v[160:163], v[144:147]
	ds_read_b128 v[160:163], v200 offset:2304
	ds_read_b128 v[188:191], v200 offset:2368
	s_cselect_b32 s85, s85, s49
	s_cmp_lt_u32 s79, 19
	s_waitcnt lgkmcnt(1)
	v_mfma_f32_16x16x32_bf16 v[140:143], v[164:167], v[160:163], v[140:143]
	v_mfma_f32_16x16x32_bf16 v[136:139], v[172:175], v[160:163], v[136:139]
	v_mfma_f32_16x16x32_bf16 v[132:135], v[176:179], v[160:163], v[132:135]
	v_mfma_f32_16x16x32_bf16 v[128:131], v[184:187], v[160:163], v[128:131]
	ds_read_b128 v[160:163], v200 offset:4608
	ds_read_b128 v[218:221], v200 offset:4672
	s_waitcnt lgkmcnt(1)
	v_mfma_f32_16x16x32_bf16 v[124:127], v[164:167], v[160:163], v[124:127]
	v_mfma_f32_16x16x32_bf16 v[120:123], v[172:175], v[160:163], v[120:123]
	v_mfma_f32_16x16x32_bf16 v[116:119], v[176:179], v[160:163], v[116:119]
	v_mfma_f32_16x16x32_bf16 v[112:115], v[184:187], v[160:163], v[112:115]
	ds_read_b128 v[160:163], v200 offset:6912
	ds_read_b128 v[222:225], v200 offset:6976
	s_waitcnt lgkmcnt(1)
	v_mfma_f32_16x16x32_bf16 v[108:111], v[164:167], v[160:163], v[108:111]
	v_mfma_f32_16x16x32_bf16 v[104:107], v[172:175], v[160:163], v[104:107]
	v_mfma_f32_16x16x32_bf16 v[100:103], v[176:179], v[160:163], v[100:103]
	v_mfma_f32_16x16x32_bf16 v[96:99], v[184:187], v[160:163], v[96:99]
	ds_read_b128 v[160:163], v200 offset:9216
	ds_read_b128 v[226:229], v200 offset:9280
	s_waitcnt lgkmcnt(1)
	v_mfma_f32_16x16x32_bf16 v[92:95], v[164:167], v[160:163], v[92:95]
	v_mfma_f32_16x16x32_bf16 v[88:91], v[172:175], v[160:163], v[88:91]
	v_mfma_f32_16x16x32_bf16 v[80:83], v[176:179], v[160:163], v[80:83]
	v_mfma_f32_16x16x32_bf16 v[84:87], v[184:187], v[160:163], v[84:87]
	ds_read_b128 v[160:163], v200 offset:11520
	ds_read_b128 v[230:233], v200 offset:11584
	s_waitcnt lgkmcnt(1)
	v_mfma_f32_16x16x32_bf16 v[76:79], v[164:167], v[160:163], v[76:79]
	v_mfma_f32_16x16x32_bf16 v[72:75], v[172:175], v[160:163], v[72:75]
	v_mfma_f32_16x16x32_bf16 v[68:71], v[176:179], v[160:163], v[68:71]
	v_mfma_f32_16x16x32_bf16 v[64:67], v[184:187], v[160:163], v[64:67]
	ds_read_b128 v[160:163], v200 offset:13824
	ds_read_b128 v[234:237], v200 offset:13888
	s_waitcnt lgkmcnt(1)
	v_mfma_f32_16x16x32_bf16 v[60:63], v[164:167], v[160:163], v[60:63]
	v_mfma_f32_16x16x32_bf16 v[56:59], v[172:175], v[160:163], v[56:59]
	v_mfma_f32_16x16x32_bf16 v[52:55], v[176:179], v[160:163], v[52:55]
	v_mfma_f32_16x16x32_bf16 v[48:51], v[184:187], v[160:163], v[48:51]
	ds_read_b128 v[160:163], v200 offset:16128
	ds_read_b128 v[238:241], v200 offset:16192
	s_waitcnt vmcnt(6)
	ds_write_b128 v202, v[4:7] offset:36864
	s_waitcnt vmcnt(5)
	ds_write_b128 v202, v[8:11] offset:46080
	s_waitcnt vmcnt(4)
	ds_write_b128 v202, v[12:15] offset:55296
	s_waitcnt vmcnt(3)
	ds_write_b128 v202, v[16:19] offset:64512
	v_mfma_f32_16x16x32_bf16 v[16:19], v[210:213], v[226:229], v[80:83]
	s_waitcnt vmcnt(3)
	ds_write_b128 v208, v[0:3]
	s_waitcnt vmcnt(2)
	ds_write_b128 v208, v[20:23] offset:9216
	s_waitcnt vmcnt(1)
	ds_write_b128 v208, v[24:27] offset:18432
	v_lshl_add_u64 v[80:81], s[82:83], 0, v[196:197]
	s_waitcnt vmcnt(0)
	ds_write_b128 v208, v[28:31] offset:27648
	v_mfma_f32_16x16x32_bf16 v[24:27], v[180:183], v[230:233], v[76:79]
	v_lshl_add_u64 v[82:83], s[84:85], 0, v[196:197]
	s_cselect_b32 s82, s52, s75
	s_cselect_b32 s83, s53, s76
	v_add_co_u32_e32 v76, vcc, s57, v80
	v_mfma_f32_16x16x32_bf16 v[28:31], v[192:195], v[230:233], v[72:75]
	s_nop 0
	v_addc_co_u32_e32 v77, vcc, 0, v81, vcc
	s_cselect_b32 s84, s54, s77
	v_add_co_u32_e32 v72, vcc, s58, v80
	s_waitcnt lgkmcnt(9)
	v_mfma_f32_16x16x32_bf16 v[40:43], v[164:167], v[160:163], v[40:43]
	v_addc_co_u32_e32 v73, vcc, 0, v81, vcc
	v_add_co_u32_e32 v74, vcc, s59, v80
	v_mfma_f32_16x16x32_bf16 v[36:39], v[172:175], v[160:163], v[36:39]
	s_nop 0
	v_addc_co_u32_e32 v75, vcc, 0, v81, vcc
	v_add_co_u32_e32 v78, vcc, s57, v82
	v_mfma_f32_16x16x32_bf16 v[32:35], v[176:179], v[160:163], v[32:35]
	s_nop 0
	v_addc_co_u32_e32 v79, vcc, 0, v83, vcc
	global_load_dwordx4 v[164:167], v[82:83], off
	v_mfma_f32_16x16x32_bf16 v[44:47], v[184:187], v[160:163], v[44:47]
	global_load_dwordx4 v[160:163], v[80:81], off
	v_add_co_u32_e32 v80, vcc, s58, v82
	v_mfma_f32_16x16x32_bf16 v[156:159], v[180:183], v[168:171], v[156:159]
	s_nop 0
	v_addc_co_u32_e32 v81, vcc, 0, v83, vcc
	v_add_co_u32_e32 v82, vcc, s59, v82
	v_mfma_f32_16x16x32_bf16 v[152:155], v[192:195], v[168:171], v[152:155]
	s_nop 0
	v_addc_co_u32_e32 v83, vcc, 0, v83, vcc
	s_cselect_b32 s85, s55, s78
	v_mfma_f32_16x16x32_bf16 v[148:151], v[210:213], v[168:171], v[148:151]
	s_add_u32 s54, s54, 0x100
	s_addc_u32 s55, s55, 0
	s_add_u32 s52, s52, 0x100
	v_mfma_f32_16x16x32_bf16 v[144:147], v[214:217], v[168:171], v[144:147]
	global_load_dwordx4 v[168:171], v[76:77], off
	global_load_dwordx4 v[172:175], v[72:73], off
	global_load_dwordx4 v[176:179], v[74:75], off
	s_addc_u32 s53, s53, 0
	s_cmp_gt_u32 s79, 19
	v_mfma_f32_16x16x32_bf16 v[140:143], v[180:183], v[188:191], v[140:143]
	s_mov_b32 s79, s80
	v_mfma_f32_16x16x32_bf16 v[136:139], v[192:195], v[188:191], v[136:139]
	v_mfma_f32_16x16x32_bf16 v[132:135], v[210:213], v[188:191], v[132:135]
	v_mfma_f32_16x16x32_bf16 v[128:131], v[214:217], v[188:191], v[128:131]
	v_mfma_f32_16x16x32_bf16 v[124:127], v[180:183], v[218:221], v[124:127]
	v_mfma_f32_16x16x32_bf16 v[108:111], v[180:183], v[222:225], v[108:111]
	v_mfma_f32_16x16x32_bf16 v[0:3], v[180:183], v[226:229], v[92:95]
	v_mfma_f32_16x16x32_bf16 v[60:63], v[180:183], v[234:237], v[60:63]
	s_waitcnt lgkmcnt(8)
	v_mfma_f32_16x16x32_bf16 v[40:43], v[180:183], v[238:241], v[40:43]
	global_load_dwordx4 v[180:183], v[78:79], off
	global_load_dwordx4 v[184:187], v[80:81], off
	global_load_dwordx4 v[188:191], v[82:83], off
	s_waitcnt lgkmcnt(0)
	s_barrier
	ds_read_b128 v[72:75], v200 offset:36864
	v_mfma_f32_16x16x32_bf16 v[116:119], v[210:213], v[218:221], v[116:119]
	v_mfma_f32_16x16x32_bf16 v[112:115], v[214:217], v[218:221], v[112:115]
	v_mfma_f32_16x16x32_bf16 v[4:7], v[210:213], v[222:225], v[100:103]
	v_mfma_f32_16x16x32_bf16 v[8:11], v[214:217], v[222:225], v[96:99]
	v_mfma_f32_16x16x32_bf16 v[20:23], v[214:217], v[226:229], v[84:87]
	v_mfma_f32_16x16x32_bf16 v[68:71], v[210:213], v[230:233], v[68:71]
	v_mfma_f32_16x16x32_bf16 v[64:67], v[214:217], v[230:233], v[64:67]
	v_mfma_f32_16x16x32_bf16 v[52:55], v[210:213], v[234:237], v[52:55]
	v_mfma_f32_16x16x32_bf16 v[48:51], v[214:217], v[234:237], v[48:51]
	v_mfma_f32_16x16x32_bf16 v[32:35], v[210:213], v[238:241], v[32:35]
	ds_read_b128 v[80:83], v209
	ds_read_b128 v[210:213], v209 offset:64
	ds_read_b128 v[84:87], v200 offset:36928
	v_mfma_f32_16x16x32_bf16 v[76:79], v[214:217], v[238:241], v[44:47]
	ds_read_b128 v[92:95], v209 offset:2304
	ds_read_b128 v[214:217], v209 offset:2368
	v_mfma_f32_16x16x32_bf16 v[120:123], v[192:195], v[218:221], v[120:123]
	ds_read_b128 v[100:103], v209 offset:4608
	ds_read_b128 v[218:221], v209 offset:4672
	s_waitcnt lgkmcnt(3)
	v_mfma_f32_16x16x32_bf16 v[96:99], v[92:95], v[72:75], v[152:155]
	s_nop 2
	ds_read_b128 v[152:155], v209 offset:6912
	ds_read_b128 v[44:47], v209 offset:6976
	v_mfma_f32_16x16x32_bf16 v[104:107], v[192:195], v[222:225], v[104:107]
	v_mfma_f32_16x16x32_bf16 v[12:15], v[192:195], v[226:229], v[88:91]
	v_mfma_f32_16x16x32_bf16 v[88:91], v[80:83], v[72:75], v[156:159]
	s_waitcnt lgkmcnt(3)
	v_mfma_f32_16x16x32_bf16 v[148:151], v[100:103], v[72:75], v[148:151]
	s_waitcnt lgkmcnt(1)
	v_mfma_f32_16x16x32_bf16 v[72:75], v[152:155], v[72:75], v[144:147]
	s_nop 2
	ds_read_b128 v[144:147], v200 offset:39168
	ds_read_b128 v[222:225], v200 offset:39232
	s_waitcnt lgkmcnt(1)
	v_mfma_f32_16x16x32_bf16 v[140:143], v[80:83], v[144:147], v[140:143]
	v_mfma_f32_16x16x32_bf16 v[136:139], v[92:95], v[144:147], v[136:139]
	v_mfma_f32_16x16x32_bf16 v[132:135], v[100:103], v[144:147], v[132:135]
	v_mfma_f32_16x16x32_bf16 v[128:131], v[152:155], v[144:147], v[128:131]
	ds_read_b128 v[144:147], v200 offset:41472
	ds_read_b128 v[226:229], v200 offset:41536
	s_waitcnt lgkmcnt(1)
	v_mfma_f32_16x16x32_bf16 v[124:127], v[80:83], v[144:147], v[124:127]
	v_mfma_f32_16x16x32_bf16 v[120:123], v[92:95], v[144:147], v[120:123]
	v_mfma_f32_16x16x32_bf16 v[116:119], v[100:103], v[144:147], v[116:119]
	v_mfma_f32_16x16x32_bf16 v[112:115], v[152:155], v[144:147], v[112:115]
	ds_read_b128 v[144:147], v200 offset:43776
	ds_read_b128 v[230:233], v200 offset:43840
	v_mfma_f32_16x16x32_bf16 v[56:59], v[192:195], v[234:237], v[56:59]
	s_waitcnt lgkmcnt(1)
	v_mfma_f32_16x16x32_bf16 v[108:111], v[80:83], v[144:147], v[108:111]
	v_mfma_f32_16x16x32_bf16 v[104:107], v[92:95], v[144:147], v[104:107]
	v_mfma_f32_16x16x32_bf16 v[4:7], v[100:103], v[144:147], v[4:7]
	v_mfma_f32_16x16x32_bf16 v[8:11], v[152:155], v[144:147], v[8:11]
	ds_read_b128 v[144:147], v200 offset:46080
	ds_read_b128 v[234:237], v200 offset:46144
	v_mfma_f32_16x16x32_bf16 v[36:39], v[192:195], v[238:241], v[36:39]
	s_waitcnt lgkmcnt(1)
	v_mfma_f32_16x16x32_bf16 v[0:3], v[80:83], v[144:147], v[0:3]
	v_mfma_f32_16x16x32_bf16 v[12:15], v[92:95], v[144:147], v[12:15]
	v_mfma_f32_16x16x32_bf16 v[16:19], v[100:103], v[144:147], v[16:19]
	v_mfma_f32_16x16x32_bf16 v[20:23], v[152:155], v[144:147], v[20:23]
	ds_read_b128 v[144:147], v200 offset:48384
	ds_read_b128 v[238:241], v200 offset:48448
	s_waitcnt lgkmcnt(1)
	v_mfma_f32_16x16x32_bf16 v[24:27], v[80:83], v[144:147], v[24:27]
	v_mfma_f32_16x16x32_bf16 v[28:31], v[92:95], v[144:147], v[28:31]
	v_mfma_f32_16x16x32_bf16 v[68:71], v[100:103], v[144:147], v[68:71]
	v_mfma_f32_16x16x32_bf16 v[64:67], v[152:155], v[144:147], v[64:67]
	ds_read_b128 v[144:147], v200 offset:50688
	ds_read_b128 v[242:245], v200 offset:50752
	s_waitcnt lgkmcnt(1)
	v_mfma_f32_16x16x32_bf16 v[60:63], v[80:83], v[144:147], v[60:63]
	v_mfma_f32_16x16x32_bf16 v[56:59], v[92:95], v[144:147], v[56:59]
	v_mfma_f32_16x16x32_bf16 v[52:55], v[100:103], v[144:147], v[52:55]
	v_mfma_f32_16x16x32_bf16 v[48:51], v[152:155], v[144:147], v[48:51]
	ds_read_b128 v[144:147], v200 offset:52992
	ds_read_b128 v[192:195], v200 offset:53056
	s_waitcnt lgkmcnt(1)
	v_mfma_f32_16x16x32_bf16 v[32:35], v[100:103], v[144:147], v[32:35]
	v_mfma_f32_16x16x32_bf16 v[100:103], v[218:221], v[230:233], v[4:7]
	s_nop 2
	v_lshl_add_u64 v[4:5], s[82:83], 0, v[196:197]
	v_mfma_f32_16x16x32_bf16 v[246:249], v[152:155], v[144:147], v[76:79]
	v_lshl_add_u64 v[6:7], s[84:85], 0, v[196:197]
	v_mfma_f32_16x16x32_bf16 v[152:155], v[214:217], v[84:87], v[96:99]
	v_mfma_f32_16x16x32_bf16 v[96:99], v[44:47], v[230:233], v[8:11]
	s_nop 2
	v_add_co_u32_e32 v8, vcc, s57, v4
	v_mfma_f32_16x16x32_bf16 v[156:159], v[210:213], v[84:87], v[88:91]
	s_nop 0
	v_addc_co_u32_e32 v9, vcc, 0, v5, vcc
	v_mfma_f32_16x16x32_bf16 v[88:91], v[214:217], v[234:237], v[12:15]
	s_nop 2
	v_add_co_u32_e32 v12, vcc, s58, v4
	v_mfma_f32_16x16x32_bf16 v[40:43], v[80:83], v[144:147], v[40:43]
	s_nop 0
	v_addc_co_u32_e32 v13, vcc, 0, v5, vcc
	v_mfma_f32_16x16x32_bf16 v[80:83], v[218:221], v[234:237], v[16:19]
	s_nop 2
	v_add_co_u32_e32 v16, vcc, s59, v4
	v_mfma_f32_16x16x32_bf16 v[36:39], v[92:95], v[144:147], v[36:39]
	s_nop 0
	v_addc_co_u32_e32 v17, vcc, 0, v5, vcc
	v_mfma_f32_16x16x32_bf16 v[148:151], v[218:221], v[84:87], v[148:151]
	v_mfma_f32_16x16x32_bf16 v[144:147], v[44:47], v[84:87], v[72:75]
	v_mfma_f32_16x16x32_bf16 v[84:87], v[44:47], v[234:237], v[20:23]
	s_nop 2
	v_add_co_u32_e32 v20, vcc, s57, v6
	v_mfma_f32_16x16x32_bf16 v[76:79], v[210:213], v[238:241], v[24:27]
	s_nop 0
	v_addc_co_u32_e32 v21, vcc, 0, v7, vcc
	s_nop 0
	v_add_co_u32_e32 v24, vcc, s58, v6
	v_mfma_f32_16x16x32_bf16 v[72:75], v[214:217], v[238:241], v[28:31]
	s_nop 0
	v_addc_co_u32_e32 v25, vcc, 0, v7, vcc
	s_nop 0
	v_add_co_u32_e32 v28, vcc, s59, v6
	v_mfma_f32_16x16x32_bf16 v[92:95], v[210:213], v[234:237], v[0:3]
	s_nop 0
	v_addc_co_u32_e32 v29, vcc, 0, v7, vcc
	s_nop 0
	global_load_dwordx4 v[0:3], v[6:7], off
	s_nop 0
	global_load_dwordx4 v[4:7], v[4:5], off
	s_nop 0
	global_load_dwordx4 v[8:11], v[8:9], off
	s_nop 0
	global_load_dwordx4 v[12:15], v[12:13], off
	s_nop 0
	global_load_dwordx4 v[16:19], v[16:17], off
	s_nop 0
	global_load_dwordx4 v[20:23], v[20:21], off
	s_nop 0
	global_load_dwordx4 v[24:27], v[24:25], off
	v_mfma_f32_16x16x32_bf16 v[140:143], v[210:213], v[222:225], v[140:143]
	global_load_dwordx4 v[28:31], v[28:29], off
	s_waitcnt vmcnt(14)
	ds_write_b128 v202, v[160:163]
	ds_write_b128 v206, v[164:167]
	s_waitcnt vmcnt(13)
	ds_write_b128 v202, v[168:171] offset:9216
	s_waitcnt vmcnt(12)
	ds_write_b128 v202, v[172:175] offset:18432
	s_waitcnt vmcnt(11)
	ds_write_b128 v202, v[176:179] offset:27648
	s_waitcnt vmcnt(10)
	ds_write_b128 v206, v[180:183] offset:9216
	s_waitcnt vmcnt(9)
	ds_write_b128 v206, v[184:187] offset:18432
	s_waitcnt vmcnt(8)
	ds_write_b128 v206, v[188:191] offset:27648
	s_waitcnt lgkmcnt(0)
	v_mfma_f32_16x16x32_bf16 v[136:139], v[214:217], v[222:225], v[136:139]
	s_barrier
	v_mfma_f32_16x16x32_bf16 v[132:135], v[218:221], v[222:225], v[132:135]
	v_mfma_f32_16x16x32_bf16 v[128:131], v[44:47], v[222:225], v[128:131]
	v_mfma_f32_16x16x32_bf16 v[124:127], v[210:213], v[226:229], v[124:127]
	v_mfma_f32_16x16x32_bf16 v[120:123], v[214:217], v[226:229], v[120:123]
	v_mfma_f32_16x16x32_bf16 v[116:119], v[218:221], v[226:229], v[116:119]
	v_mfma_f32_16x16x32_bf16 v[112:115], v[44:47], v[226:229], v[112:115]
	v_mfma_f32_16x16x32_bf16 v[108:111], v[210:213], v[230:233], v[108:111]
	v_mfma_f32_16x16x32_bf16 v[104:107], v[214:217], v[230:233], v[104:107]
	v_mfma_f32_16x16x32_bf16 v[68:71], v[218:221], v[238:241], v[68:71]
	v_mfma_f32_16x16x32_bf16 v[64:67], v[44:47], v[238:241], v[64:67]
	v_mfma_f32_16x16x32_bf16 v[60:63], v[210:213], v[242:245], v[60:63]
	v_mfma_f32_16x16x32_bf16 v[56:59], v[214:217], v[242:245], v[56:59]
	v_mfma_f32_16x16x32_bf16 v[52:55], v[218:221], v[242:245], v[52:55]
	v_mfma_f32_16x16x32_bf16 v[48:51], v[44:47], v[242:245], v[48:51]
	v_mfma_f32_16x16x32_bf16 v[40:43], v[210:213], v[192:195], v[40:43]
	v_mfma_f32_16x16x32_bf16 v[36:39], v[214:217], v[192:195], v[36:39]
	v_mfma_f32_16x16x32_bf16 v[32:35], v[218:221], v[192:195], v[32:35]
	v_mfma_f32_16x16x32_bf16 v[44:47], v[44:47], v[192:195], v[246:249]
	s_cbranch_scc0 .LBB0_1208
	s_cmp_eq_u32 s72, 0
	s_mov_b32 s99, 0x6a44000
	s_cselect_b32 s99, s99, 0x7a44000
	s_lshl_b32 s98, s74, 11
	s_lshl_b32 s100, s73, 1
	s_add_u32 s98, s98, s100
	s_add_u32 s98, s98, s99
	s_add_u32 s100, s34, s98
	s_addc_u32 s101, s35, 0
	v_and_b32_e32 v160, 15, v207
	v_and_b32_e32 v161, 0x80, v203
	v_add_u32_e32 v160, v160, v161
	v_lshlrev_b32_e32 v160, 11, v160
	v_and_b32_e32 v161, 0xc0, v207
	v_lshl_add_u32 v160, v161, 1, v160
	v_and_b32_e32 v161, 4, v203
	v_lshl_add_u32 v160, v161, 3, v160
	v_and_b32_e32 v161, 8, v203
	v_lshl_add_u32 v160, v161, 1, v160
	v_cvt_pk_bf16_f32 v156, v156, v157
	v_cvt_pk_bf16_f32 v157, v158, v159
	v_cvt_pk_bf16_f32 v158, v152, v153
	v_cvt_pk_bf16_f32 v159, v154, v155
	v_cvt_pk_bf16_f32 v148, v148, v149
	v_cvt_pk_bf16_f32 v149, v150, v151
	v_cvt_pk_bf16_f32 v150, v144, v145
	v_cvt_pk_bf16_f32 v151, v146, v147
	v_permlane16_swap_b32_e32 v156, v158
	v_permlane16_swap_b32_e32 v157, v159
	v_permlane16_swap_b32_e32 v148, v150
	v_permlane16_swap_b32_e32 v149, v151
	global_store_dwordx4 v160, v[156:159], s[100:101] sc1
	global_store_dwordx4 v160, v[148:151], s[100:101] offset:64 sc1
	s_add_u32 s100, s100, 0x8000
	s_addc_u32 s101, s101, 0
	v_cvt_pk_bf16_f32 v140, v140, v141
	v_cvt_pk_bf16_f32 v141, v142, v143
	v_cvt_pk_bf16_f32 v142, v136, v137
	v_cvt_pk_bf16_f32 v143, v138, v139
	v_cvt_pk_bf16_f32 v132, v132, v133
	v_cvt_pk_bf16_f32 v133, v134, v135
	v_cvt_pk_bf16_f32 v134, v128, v129
	v_cvt_pk_bf16_f32 v135, v130, v131
	v_permlane16_swap_b32_e32 v140, v142
	v_permlane16_swap_b32_e32 v141, v143
	v_permlane16_swap_b32_e32 v132, v134
	v_permlane16_swap_b32_e32 v133, v135
	global_store_dwordx4 v160, v[140:143], s[100:101] sc1
	global_store_dwordx4 v160, v[132:135], s[100:101] offset:64 sc1
	s_add_u32 s100, s100, 0x8000
	s_addc_u32 s101, s101, 0
	v_cvt_pk_bf16_f32 v124, v124, v125
	v_cvt_pk_bf16_f32 v125, v126, v127
	v_cvt_pk_bf16_f32 v126, v120, v121
	v_cvt_pk_bf16_f32 v127, v122, v123
	v_cvt_pk_bf16_f32 v116, v116, v117
	v_cvt_pk_bf16_f32 v117, v118, v119
	v_cvt_pk_bf16_f32 v118, v112, v113
	v_cvt_pk_bf16_f32 v119, v114, v115
	v_permlane16_swap_b32_e32 v124, v126
	v_permlane16_swap_b32_e32 v125, v127
	v_permlane16_swap_b32_e32 v116, v118
	v_permlane16_swap_b32_e32 v117, v119
	global_store_dwordx4 v160, v[124:127], s[100:101] sc1
	global_store_dwordx4 v160, v[116:119], s[100:101] offset:64 sc1
	s_add_u32 s100, s100, 0x8000
	s_addc_u32 s101, s101, 0
	v_cvt_pk_bf16_f32 v108, v108, v109
	v_cvt_pk_bf16_f32 v109, v110, v111
	v_cvt_pk_bf16_f32 v110, v104, v105
	v_cvt_pk_bf16_f32 v111, v106, v107
	v_cvt_pk_bf16_f32 v100, v100, v101
	v_cvt_pk_bf16_f32 v101, v102, v103
	v_cvt_pk_bf16_f32 v102, v96, v97
	v_cvt_pk_bf16_f32 v103, v98, v99
	v_permlane16_swap_b32_e32 v108, v110
	v_permlane16_swap_b32_e32 v109, v111
	v_permlane16_swap_b32_e32 v100, v102
	v_permlane16_swap_b32_e32 v101, v103
	global_store_dwordx4 v160, v[108:111], s[100:101] sc1
	global_store_dwordx4 v160, v[100:103], s[100:101] offset:64 sc1
	s_add_u32 s100, s100, 0x8000
	s_addc_u32 s101, s101, 0
	v_cvt_pk_bf16_f32 v92, v92, v93
	v_cvt_pk_bf16_f32 v93, v94, v95
	v_cvt_pk_bf16_f32 v94, v88, v89
	v_cvt_pk_bf16_f32 v95, v90, v91
	v_cvt_pk_bf16_f32 v80, v80, v81
	v_cvt_pk_bf16_f32 v81, v82, v83
	v_cvt_pk_bf16_f32 v82, v84, v85
	v_cvt_pk_bf16_f32 v83, v86, v87
	v_permlane16_swap_b32_e32 v92, v94
	v_permlane16_swap_b32_e32 v93, v95
	v_permlane16_swap_b32_e32 v80, v82
	v_permlane16_swap_b32_e32 v81, v83
	global_store_dwordx4 v160, v[92:95], s[100:101] sc1
	global_store_dwordx4 v160, v[80:83], s[100:101] offset:64 sc1
	s_add_u32 s100, s100, 0x8000
	s_addc_u32 s101, s101, 0
	v_cvt_pk_bf16_f32 v76, v76, v77
	v_cvt_pk_bf16_f32 v77, v78, v79
	v_cvt_pk_bf16_f32 v78, v72, v73
	v_cvt_pk_bf16_f32 v79, v74, v75
	v_cvt_pk_bf16_f32 v68, v68, v69
	v_cvt_pk_bf16_f32 v69, v70, v71
	v_cvt_pk_bf16_f32 v70, v64, v65
	v_cvt_pk_bf16_f32 v71, v66, v67
	v_permlane16_swap_b32_e32 v76, v78
	v_permlane16_swap_b32_e32 v77, v79
	v_permlane16_swap_b32_e32 v68, v70
	v_permlane16_swap_b32_e32 v69, v71
	global_store_dwordx4 v160, v[76:79], s[100:101] sc1
	global_store_dwordx4 v160, v[68:71], s[100:101] offset:64 sc1
	s_add_u32 s100, s100, 0x8000
	s_addc_u32 s101, s101, 0
	v_cvt_pk_bf16_f32 v60, v60, v61
	v_cvt_pk_bf16_f32 v61, v62, v63
	v_cvt_pk_bf16_f32 v62, v56, v57
	v_cvt_pk_bf16_f32 v63, v58, v59
	v_cvt_pk_bf16_f32 v52, v52, v53
	v_cvt_pk_bf16_f32 v53, v54, v55
	v_cvt_pk_bf16_f32 v54, v48, v49
	v_cvt_pk_bf16_f32 v55, v50, v51
	v_permlane16_swap_b32_e32 v60, v62
	v_permlane16_swap_b32_e32 v61, v63
	v_permlane16_swap_b32_e32 v52, v54
	v_permlane16_swap_b32_e32 v53, v55
	global_store_dwordx4 v160, v[60:63], s[100:101] sc1
	global_store_dwordx4 v160, v[52:55], s[100:101] offset:64 sc1
	s_add_u32 s100, s100, 0x8000
	s_addc_u32 s101, s101, 0
	v_cvt_pk_bf16_f32 v40, v40, v41
	v_cvt_pk_bf16_f32 v41, v42, v43
	v_cvt_pk_bf16_f32 v42, v36, v37
	v_cvt_pk_bf16_f32 v43, v38, v39
	v_cvt_pk_bf16_f32 v32, v32, v33
	v_cvt_pk_bf16_f32 v33, v34, v35
	v_cvt_pk_bf16_f32 v34, v44, v45
	v_cvt_pk_bf16_f32 v35, v46, v47
	v_permlane16_swap_b32_e32 v40, v42
	v_permlane16_swap_b32_e32 v41, v43
	v_permlane16_swap_b32_e32 v32, v34
	v_permlane16_swap_b32_e32 v33, v35
	global_store_dwordx4 v160, v[40:43], s[100:101] sc1
	global_store_dwordx4 v160, v[32:35], s[100:101] offset:64 sc1
	s_and_b64 vcc, exec, s[50:51]
	s_mov_b32 s72, s71
	s_mov_b32 s73, s70
	s_mov_b32 s74, s69
	s_mov_b64 s[54:55], s[48:49]
	s_mov_b64 s[52:53], s[44:45]
	s_cbranch_vccz .LBB0_1205
	s_load_dwordx16 s[36:51], s[0:1], 0xc0

.LBB0_1511:
	ds_read_b128 v[160:163], v200
	ds_read_b128 v[164:167], v201
	ds_read_b128 v[180:183], v201 offset:64
	ds_read_b128 v[168:171], v200 offset:64
	ds_read_b128 v[172:175], v201 offset:2304
	ds_read_b128 v[192:195], v201 offset:2368
	ds_read_b128 v[176:179], v201 offset:4608
	ds_read_b128 v[210:213], v201 offset:4672
	ds_read_b128 v[184:187], v201 offset:6912
	ds_read_b128 v[214:217], v201 offset:6976
	s_waitcnt lgkmcnt(8)
	v_mfma_f32_16x16x32_bf16 v[156:159], v[164:167], v[160:163], v[156:159]
	s_add_i32 s86, s85, 2
	s_add_u32 s87, s56, 0xffffff80
	s_addc_u32 s93, s57, -1
	s_waitcnt lgkmcnt(5)
	v_mfma_f32_16x16x32_bf16 v[152:155], v[172:175], v[160:163], v[152:155]
	s_add_u32 s94, s58, 0xffffff80
	s_addc_u32 s95, s59, -1
	s_cmp_lt_u32 s85, 20
	s_waitcnt lgkmcnt(3)
	v_mfma_f32_16x16x32_bf16 v[148:151], v[176:179], v[160:163], v[148:151]
	s_cselect_b32 s92, s87, s50
	s_cselect_b32 s93, s93, s51
	s_cselect_b32 s94, s94, s52
	s_waitcnt lgkmcnt(1)
	v_mfma_f32_16x16x32_bf16 v[144:147], v[184:187], v[160:163], v[144:147]
	ds_read_b128 v[160:163], v200 offset:2304
	ds_read_b128 v[188:191], v200 offset:2368
	s_cselect_b32 s95, s95, s53
	s_cmp_lt_u32 s85, 19
	s_waitcnt lgkmcnt(1)
	v_mfma_f32_16x16x32_bf16 v[140:143], v[164:167], v[160:163], v[140:143]
	v_mfma_f32_16x16x32_bf16 v[136:139], v[172:175], v[160:163], v[136:139]
	v_mfma_f32_16x16x32_bf16 v[132:135], v[176:179], v[160:163], v[132:135]
	v_mfma_f32_16x16x32_bf16 v[128:131], v[184:187], v[160:163], v[128:131]
	ds_read_b128 v[160:163], v200 offset:4608
	ds_read_b128 v[218:221], v200 offset:4672
	s_waitcnt lgkmcnt(1)
	v_mfma_f32_16x16x32_bf16 v[124:127], v[164:167], v[160:163], v[124:127]
	v_mfma_f32_16x16x32_bf16 v[120:123], v[172:175], v[160:163], v[120:123]
	v_mfma_f32_16x16x32_bf16 v[116:119], v[176:179], v[160:163], v[116:119]
	v_mfma_f32_16x16x32_bf16 v[112:115], v[184:187], v[160:163], v[112:115]
	ds_read_b128 v[160:163], v200 offset:6912
	ds_read_b128 v[222:225], v200 offset:6976
	s_waitcnt lgkmcnt(1)
	v_mfma_f32_16x16x32_bf16 v[108:111], v[164:167], v[160:163], v[108:111]
	v_mfma_f32_16x16x32_bf16 v[104:107], v[172:175], v[160:163], v[104:107]
	v_mfma_f32_16x16x32_bf16 v[100:103], v[176:179], v[160:163], v[100:103]
	v_mfma_f32_16x16x32_bf16 v[96:99], v[184:187], v[160:163], v[96:99]
	ds_read_b128 v[160:163], v200 offset:9216
	ds_read_b128 v[226:229], v200 offset:9280
	s_waitcnt lgkmcnt(1)
	v_mfma_f32_16x16x32_bf16 v[92:95], v[164:167], v[160:163], v[92:95]
	v_mfma_f32_16x16x32_bf16 v[88:91], v[172:175], v[160:163], v[88:91]
	v_mfma_f32_16x16x32_bf16 v[80:83], v[176:179], v[160:163], v[80:83]
	v_mfma_f32_16x16x32_bf16 v[84:87], v[184:187], v[160:163], v[84:87]
	ds_read_b128 v[160:163], v200 offset:11520
	ds_read_b128 v[230:233], v200 offset:11584
	s_waitcnt lgkmcnt(1)
	v_mfma_f32_16x16x32_bf16 v[76:79], v[164:167], v[160:163], v[76:79]
	v_mfma_f32_16x16x32_bf16 v[72:75], v[172:175], v[160:163], v[72:75]
	v_mfma_f32_16x16x32_bf16 v[68:71], v[176:179], v[160:163], v[68:71]
	v_mfma_f32_16x16x32_bf16 v[64:67], v[184:187], v[160:163], v[64:67]
	ds_read_b128 v[160:163], v200 offset:13824
	ds_read_b128 v[234:237], v200 offset:13888
	s_waitcnt lgkmcnt(1)
	v_mfma_f32_16x16x32_bf16 v[60:63], v[164:167], v[160:163], v[60:63]
	v_mfma_f32_16x16x32_bf16 v[56:59], v[172:175], v[160:163], v[56:59]
	v_mfma_f32_16x16x32_bf16 v[52:55], v[176:179], v[160:163], v[52:55]
	v_mfma_f32_16x16x32_bf16 v[48:51], v[184:187], v[160:163], v[48:51]
	ds_read_b128 v[160:163], v200 offset:16128
	ds_read_b128 v[238:241], v200 offset:16192
	s_waitcnt vmcnt(6)
	ds_write_b128 v202, v[4:7] offset:36864
	s_waitcnt vmcnt(5)
	ds_write_b128 v202, v[8:11] offset:46080
	s_waitcnt vmcnt(4)
	ds_write_b128 v202, v[12:15] offset:55296
	s_waitcnt vmcnt(3)
	ds_write_b128 v202, v[16:19] offset:64512
	v_mfma_f32_16x16x32_bf16 v[16:19], v[210:213], v[226:229], v[80:83]
	s_waitcnt vmcnt(3)
	ds_write_b128 v208, v[0:3]
	s_waitcnt vmcnt(2)
	ds_write_b128 v208, v[20:23] offset:9216
	s_waitcnt vmcnt(1)
	ds_write_b128 v208, v[24:27] offset:18432
	v_lshl_add_u64 v[80:81], s[92:93], 0, v[196:197]
	s_waitcnt vmcnt(0)
	ds_write_b128 v208, v[28:31] offset:27648
	v_mfma_f32_16x16x32_bf16 v[24:27], v[180:183], v[230:233], v[76:79]
	v_lshl_add_u64 v[82:83], s[94:95], 0, v[196:197]
	s_cselect_b32 s92, s56, s81
	s_cselect_b32 s93, s57, s82
	v_add_co_u32_e32 v76, vcc, s61, v80
	v_mfma_f32_16x16x32_bf16 v[28:31], v[192:195], v[230:233], v[72:75]
	s_nop 0
	v_addc_co_u32_e32 v77, vcc, 0, v81, vcc
	s_cselect_b32 s94, s58, s83
	v_add_co_u32_e32 v72, vcc, s62, v80
	s_waitcnt lgkmcnt(9)
	v_mfma_f32_16x16x32_bf16 v[40:43], v[164:167], v[160:163], v[40:43]
	v_addc_co_u32_e32 v73, vcc, 0, v81, vcc
	v_add_co_u32_e32 v74, vcc, s63, v80
	v_mfma_f32_16x16x32_bf16 v[36:39], v[172:175], v[160:163], v[36:39]
	s_nop 0
	v_addc_co_u32_e32 v75, vcc, 0, v81, vcc
	v_add_co_u32_e32 v78, vcc, s61, v82
	v_mfma_f32_16x16x32_bf16 v[32:35], v[176:179], v[160:163], v[32:35]
	s_nop 0
	v_addc_co_u32_e32 v79, vcc, 0, v83, vcc
	global_load_dwordx4 v[164:167], v[82:83], off
	v_mfma_f32_16x16x32_bf16 v[44:47], v[184:187], v[160:163], v[44:47]
	global_load_dwordx4 v[160:163], v[80:81], off
	v_add_co_u32_e32 v80, vcc, s62, v82
	v_mfma_f32_16x16x32_bf16 v[156:159], v[180:183], v[168:171], v[156:159]
	s_nop 0
	v_addc_co_u32_e32 v81, vcc, 0, v83, vcc
	v_add_co_u32_e32 v82, vcc, s63, v82
	v_mfma_f32_16x16x32_bf16 v[152:155], v[192:195], v[168:171], v[152:155]
	s_nop 0
	v_addc_co_u32_e32 v83, vcc, 0, v83, vcc
	s_cselect_b32 s95, s59, s84
	v_mfma_f32_16x16x32_bf16 v[148:151], v[210:213], v[168:171], v[148:151]
	s_add_u32 s58, s58, 0x100
	s_addc_u32 s59, s59, 0
	s_add_u32 s56, s56, 0x100
	v_mfma_f32_16x16x32_bf16 v[144:147], v[214:217], v[168:171], v[144:147]
	global_load_dwordx4 v[168:171], v[76:77], off
	global_load_dwordx4 v[172:175], v[72:73], off
	global_load_dwordx4 v[176:179], v[74:75], off
	s_addc_u32 s57, s57, 0
	s_cmp_gt_u32 s85, 19
	v_mfma_f32_16x16x32_bf16 v[140:143], v[180:183], v[188:191], v[140:143]
	s_mov_b32 s85, s86
	v_mfma_f32_16x16x32_bf16 v[136:139], v[192:195], v[188:191], v[136:139]
	v_mfma_f32_16x16x32_bf16 v[132:135], v[210:213], v[188:191], v[132:135]
	v_mfma_f32_16x16x32_bf16 v[128:131], v[214:217], v[188:191], v[128:131]
	v_mfma_f32_16x16x32_bf16 v[124:127], v[180:183], v[218:221], v[124:127]
	v_mfma_f32_16x16x32_bf16 v[108:111], v[180:183], v[222:225], v[108:111]
	v_mfma_f32_16x16x32_bf16 v[0:3], v[180:183], v[226:229], v[92:95]
	v_mfma_f32_16x16x32_bf16 v[60:63], v[180:183], v[234:237], v[60:63]
	s_waitcnt lgkmcnt(8)
	v_mfma_f32_16x16x32_bf16 v[40:43], v[180:183], v[238:241], v[40:43]
	global_load_dwordx4 v[180:183], v[78:79], off
	global_load_dwordx4 v[184:187], v[80:81], off
	global_load_dwordx4 v[188:191], v[82:83], off
	s_waitcnt lgkmcnt(0)
	s_barrier
	ds_read_b128 v[72:75], v200 offset:36864
	v_mfma_f32_16x16x32_bf16 v[116:119], v[210:213], v[218:221], v[116:119]
	v_mfma_f32_16x16x32_bf16 v[112:115], v[214:217], v[218:221], v[112:115]
	v_mfma_f32_16x16x32_bf16 v[4:7], v[210:213], v[222:225], v[100:103]
	v_mfma_f32_16x16x32_bf16 v[8:11], v[214:217], v[222:225], v[96:99]
	v_mfma_f32_16x16x32_bf16 v[20:23], v[214:217], v[226:229], v[84:87]
	v_mfma_f32_16x16x32_bf16 v[68:71], v[210:213], v[230:233], v[68:71]
	v_mfma_f32_16x16x32_bf16 v[64:67], v[214:217], v[230:233], v[64:67]
	v_mfma_f32_16x16x32_bf16 v[52:55], v[210:213], v[234:237], v[52:55]
	v_mfma_f32_16x16x32_bf16 v[48:51], v[214:217], v[234:237], v[48:51]
	v_mfma_f32_16x16x32_bf16 v[32:35], v[210:213], v[238:241], v[32:35]
	ds_read_b128 v[80:83], v209
	ds_read_b128 v[210:213], v209 offset:64
	ds_read_b128 v[84:87], v200 offset:36928
	v_mfma_f32_16x16x32_bf16 v[76:79], v[214:217], v[238:241], v[44:47]
	ds_read_b128 v[92:95], v209 offset:2304
	ds_read_b128 v[214:217], v209 offset:2368
	v_mfma_f32_16x16x32_bf16 v[120:123], v[192:195], v[218:221], v[120:123]
	ds_read_b128 v[100:103], v209 offset:4608
	ds_read_b128 v[218:221], v209 offset:4672
	s_waitcnt lgkmcnt(3)
	v_mfma_f32_16x16x32_bf16 v[96:99], v[92:95], v[72:75], v[152:155]
	s_nop 2
	ds_read_b128 v[152:155], v209 offset:6912
	ds_read_b128 v[44:47], v209 offset:6976
	v_mfma_f32_16x16x32_bf16 v[104:107], v[192:195], v[222:225], v[104:107]
	v_mfma_f32_16x16x32_bf16 v[12:15], v[192:195], v[226:229], v[88:91]
	v_mfma_f32_16x16x32_bf16 v[88:91], v[80:83], v[72:75], v[156:159]
	s_waitcnt lgkmcnt(3)
	v_mfma_f32_16x16x32_bf16 v[148:151], v[100:103], v[72:75], v[148:151]
	s_waitcnt lgkmcnt(1)
	v_mfma_f32_16x16x32_bf16 v[72:75], v[152:155], v[72:75], v[144:147]
	s_nop 2
	ds_read_b128 v[144:147], v200 offset:39168
	ds_read_b128 v[222:225], v200 offset:39232
	s_waitcnt lgkmcnt(1)
	v_mfma_f32_16x16x32_bf16 v[140:143], v[80:83], v[144:147], v[140:143]
	v_mfma_f32_16x16x32_bf16 v[136:139], v[92:95], v[144:147], v[136:139]
	v_mfma_f32_16x16x32_bf16 v[132:135], v[100:103], v[144:147], v[132:135]
	v_mfma_f32_16x16x32_bf16 v[128:131], v[152:155], v[144:147], v[128:131]
	ds_read_b128 v[144:147], v200 offset:41472
	ds_read_b128 v[226:229], v200 offset:41536
	s_waitcnt lgkmcnt(1)
	v_mfma_f32_16x16x32_bf16 v[124:127], v[80:83], v[144:147], v[124:127]
	v_mfma_f32_16x16x32_bf16 v[120:123], v[92:95], v[144:147], v[120:123]
	v_mfma_f32_16x16x32_bf16 v[116:119], v[100:103], v[144:147], v[116:119]
	v_mfma_f32_16x16x32_bf16 v[112:115], v[152:155], v[144:147], v[112:115]
	ds_read_b128 v[144:147], v200 offset:43776
	ds_read_b128 v[230:233], v200 offset:43840
	v_mfma_f32_16x16x32_bf16 v[56:59], v[192:195], v[234:237], v[56:59]
	s_waitcnt lgkmcnt(1)
	v_mfma_f32_16x16x32_bf16 v[108:111], v[80:83], v[144:147], v[108:111]
	v_mfma_f32_16x16x32_bf16 v[104:107], v[92:95], v[144:147], v[104:107]
	v_mfma_f32_16x16x32_bf16 v[4:7], v[100:103], v[144:147], v[4:7]
	v_mfma_f32_16x16x32_bf16 v[8:11], v[152:155], v[144:147], v[8:11]
	ds_read_b128 v[144:147], v200 offset:46080
	ds_read_b128 v[234:237], v200 offset:46144
	v_mfma_f32_16x16x32_bf16 v[36:39], v[192:195], v[238:241], v[36:39]
	s_waitcnt lgkmcnt(1)
	v_mfma_f32_16x16x32_bf16 v[0:3], v[80:83], v[144:147], v[0:3]
	v_mfma_f32_16x16x32_bf16 v[12:15], v[92:95], v[144:147], v[12:15]
	v_mfma_f32_16x16x32_bf16 v[16:19], v[100:103], v[144:147], v[16:19]
	v_mfma_f32_16x16x32_bf16 v[20:23], v[152:155], v[144:147], v[20:23]
	ds_read_b128 v[144:147], v200 offset:48384
	ds_read_b128 v[238:241], v200 offset:48448
	s_waitcnt lgkmcnt(1)
	v_mfma_f32_16x16x32_bf16 v[24:27], v[80:83], v[144:147], v[24:27]
	v_mfma_f32_16x16x32_bf16 v[28:31], v[92:95], v[144:147], v[28:31]
	v_mfma_f32_16x16x32_bf16 v[68:71], v[100:103], v[144:147], v[68:71]
	v_mfma_f32_16x16x32_bf16 v[64:67], v[152:155], v[144:147], v[64:67]
	ds_read_b128 v[144:147], v200 offset:50688
	ds_read_b128 v[242:245], v200 offset:50752
	s_waitcnt lgkmcnt(1)
	v_mfma_f32_16x16x32_bf16 v[60:63], v[80:83], v[144:147], v[60:63]
	v_mfma_f32_16x16x32_bf16 v[56:59], v[92:95], v[144:147], v[56:59]
	v_mfma_f32_16x16x32_bf16 v[52:55], v[100:103], v[144:147], v[52:55]
	v_mfma_f32_16x16x32_bf16 v[48:51], v[152:155], v[144:147], v[48:51]
	ds_read_b128 v[144:147], v200 offset:52992
	ds_read_b128 v[192:195], v200 offset:53056
	s_waitcnt lgkmcnt(1)
	v_mfma_f32_16x16x32_bf16 v[32:35], v[100:103], v[144:147], v[32:35]
	v_mfma_f32_16x16x32_bf16 v[100:103], v[218:221], v[230:233], v[4:7]
	s_nop 2
	v_lshl_add_u64 v[4:5], s[92:93], 0, v[196:197]
	v_mfma_f32_16x16x32_bf16 v[246:249], v[152:155], v[144:147], v[76:79]
	v_lshl_add_u64 v[6:7], s[94:95], 0, v[196:197]
	v_mfma_f32_16x16x32_bf16 v[152:155], v[214:217], v[84:87], v[96:99]
	v_mfma_f32_16x16x32_bf16 v[96:99], v[44:47], v[230:233], v[8:11]
	s_nop 2
	v_add_co_u32_e32 v8, vcc, s61, v4
	v_mfma_f32_16x16x32_bf16 v[156:159], v[210:213], v[84:87], v[88:91]
	s_nop 0
	v_addc_co_u32_e32 v9, vcc, 0, v5, vcc
	v_mfma_f32_16x16x32_bf16 v[88:91], v[214:217], v[234:237], v[12:15]
	s_nop 2
	v_add_co_u32_e32 v12, vcc, s62, v4
	v_mfma_f32_16x16x32_bf16 v[40:43], v[80:83], v[144:147], v[40:43]
	s_nop 0
	v_addc_co_u32_e32 v13, vcc, 0, v5, vcc
	v_mfma_f32_16x16x32_bf16 v[80:83], v[218:221], v[234:237], v[16:19]
	s_nop 2
	v_add_co_u32_e32 v16, vcc, s63, v4
	v_mfma_f32_16x16x32_bf16 v[36:39], v[92:95], v[144:147], v[36:39]
	s_nop 0
	v_addc_co_u32_e32 v17, vcc, 0, v5, vcc
	v_mfma_f32_16x16x32_bf16 v[148:151], v[218:221], v[84:87], v[148:151]
	v_mfma_f32_16x16x32_bf16 v[144:147], v[44:47], v[84:87], v[72:75]
	v_mfma_f32_16x16x32_bf16 v[84:87], v[44:47], v[234:237], v[20:23]
	s_nop 2
	v_add_co_u32_e32 v20, vcc, s61, v6
	v_mfma_f32_16x16x32_bf16 v[76:79], v[210:213], v[238:241], v[24:27]
	s_nop 0
	v_addc_co_u32_e32 v21, vcc, 0, v7, vcc
	s_nop 0
	v_add_co_u32_e32 v24, vcc, s62, v6
	v_mfma_f32_16x16x32_bf16 v[72:75], v[214:217], v[238:241], v[28:31]
	s_nop 0
	v_addc_co_u32_e32 v25, vcc, 0, v7, vcc
	s_nop 0
	v_add_co_u32_e32 v28, vcc, s63, v6
	v_mfma_f32_16x16x32_bf16 v[92:95], v[210:213], v[234:237], v[0:3]
	s_nop 0
	v_addc_co_u32_e32 v29, vcc, 0, v7, vcc
	s_nop 0
	global_load_dwordx4 v[0:3], v[6:7], off
	s_nop 0
	global_load_dwordx4 v[4:7], v[4:5], off
	s_nop 0
	global_load_dwordx4 v[8:11], v[8:9], off
	s_nop 0
	global_load_dwordx4 v[12:15], v[12:13], off
	s_nop 0
	global_load_dwordx4 v[16:19], v[16:17], off
	s_nop 0
	global_load_dwordx4 v[20:23], v[20:21], off
	s_nop 0
	global_load_dwordx4 v[24:27], v[24:25], off
	v_mfma_f32_16x16x32_bf16 v[140:143], v[210:213], v[222:225], v[140:143]
	global_load_dwordx4 v[28:31], v[28:29], off
	s_waitcnt vmcnt(14)
	ds_write_b128 v202, v[160:163]
	ds_write_b128 v206, v[164:167]
	s_waitcnt vmcnt(13)
	ds_write_b128 v202, v[168:171] offset:9216
	s_waitcnt vmcnt(12)
	ds_write_b128 v202, v[172:175] offset:18432
	s_waitcnt vmcnt(11)
	ds_write_b128 v202, v[176:179] offset:27648
	s_waitcnt vmcnt(10)
	ds_write_b128 v206, v[180:183] offset:9216
	s_waitcnt vmcnt(9)
	ds_write_b128 v206, v[184:187] offset:18432
	s_waitcnt vmcnt(8)
	ds_write_b128 v206, v[188:191] offset:27648
	s_waitcnt lgkmcnt(0)
	v_mfma_f32_16x16x32_bf16 v[136:139], v[214:217], v[222:225], v[136:139]
	s_barrier
	v_mfma_f32_16x16x32_bf16 v[132:135], v[218:221], v[222:225], v[132:135]
	v_mfma_f32_16x16x32_bf16 v[128:131], v[44:47], v[222:225], v[128:131]
	v_mfma_f32_16x16x32_bf16 v[124:127], v[210:213], v[226:229], v[124:127]
	v_mfma_f32_16x16x32_bf16 v[120:123], v[214:217], v[226:229], v[120:123]
	v_mfma_f32_16x16x32_bf16 v[116:119], v[218:221], v[226:229], v[116:119]
	v_mfma_f32_16x16x32_bf16 v[112:115], v[44:47], v[226:229], v[112:115]
	v_mfma_f32_16x16x32_bf16 v[108:111], v[210:213], v[230:233], v[108:111]
	v_mfma_f32_16x16x32_bf16 v[104:107], v[214:217], v[230:233], v[104:107]
	v_mfma_f32_16x16x32_bf16 v[68:71], v[218:221], v[238:241], v[68:71]
	v_mfma_f32_16x16x32_bf16 v[64:67], v[44:47], v[238:241], v[64:67]
	v_mfma_f32_16x16x32_bf16 v[60:63], v[210:213], v[242:245], v[60:63]
	v_mfma_f32_16x16x32_bf16 v[56:59], v[214:217], v[242:245], v[56:59]
	v_mfma_f32_16x16x32_bf16 v[52:55], v[218:221], v[242:245], v[52:55]
	v_mfma_f32_16x16x32_bf16 v[48:51], v[44:47], v[242:245], v[48:51]
	v_mfma_f32_16x16x32_bf16 v[40:43], v[210:213], v[192:195], v[40:43]
	v_mfma_f32_16x16x32_bf16 v[36:39], v[214:217], v[192:195], v[36:39]
	v_mfma_f32_16x16x32_bf16 v[32:35], v[218:221], v[192:195], v[32:35]
	v_mfma_f32_16x16x32_bf16 v[44:47], v[44:47], v[192:195], v[246:249]
	s_cbranch_scc0 .LBB0_1511
	s_cmp_eq_u32 s78, 0
	s_mov_b32 s99, 0x6a44000
	s_cselect_b32 s99, s99, 0x7a44000
	s_lshl_b32 s98, s80, 11
	s_lshl_b32 s100, s79, 1
	s_add_u32 s98, s98, s100
	s_add_u32 s98, s98, s99
	s_add_u32 s100, s34, s98
	s_addc_u32 s101, s35, 0
	v_and_b32_e32 v160, 15, v207
	v_and_b32_e32 v161, 0x80, v203
	v_add_u32_e32 v160, v160, v161
	v_lshlrev_b32_e32 v160, 11, v160
	v_and_b32_e32 v161, 0xc0, v207
	v_lshl_add_u32 v160, v161, 1, v160
	v_and_b32_e32 v161, 4, v203
	v_lshl_add_u32 v160, v161, 3, v160
	v_and_b32_e32 v161, 8, v203
	v_lshl_add_u32 v160, v161, 1, v160
	v_cvt_pk_bf16_f32 v156, v156, v157
	v_cvt_pk_bf16_f32 v157, v158, v159
	v_cvt_pk_bf16_f32 v158, v152, v153
	v_cvt_pk_bf16_f32 v159, v154, v155
	v_cvt_pk_bf16_f32 v148, v148, v149
	v_cvt_pk_bf16_f32 v149, v150, v151
	v_cvt_pk_bf16_f32 v150, v144, v145
	v_cvt_pk_bf16_f32 v151, v146, v147
	v_permlane16_swap_b32_e32 v156, v158
	v_permlane16_swap_b32_e32 v157, v159
	v_permlane16_swap_b32_e32 v148, v150
	v_permlane16_swap_b32_e32 v149, v151
	global_store_dwordx4 v160, v[156:159], s[100:101] sc1
	global_store_dwordx4 v160, v[148:151], s[100:101] offset:64 sc1
	s_add_u32 s100, s100, 0x8000
	s_addc_u32 s101, s101, 0
	v_cvt_pk_bf16_f32 v140, v140, v141
	v_cvt_pk_bf16_f32 v141, v142, v143
	v_cvt_pk_bf16_f32 v142, v136, v137
	v_cvt_pk_bf16_f32 v143, v138, v139
	v_cvt_pk_bf16_f32 v132, v132, v133
	v_cvt_pk_bf16_f32 v133, v134, v135
	v_cvt_pk_bf16_f32 v134, v128, v129
	v_cvt_pk_bf16_f32 v135, v130, v131
	v_permlane16_swap_b32_e32 v140, v142
	v_permlane16_swap_b32_e32 v141, v143
	v_permlane16_swap_b32_e32 v132, v134
	v_permlane16_swap_b32_e32 v133, v135
	global_store_dwordx4 v160, v[140:143], s[100:101] sc1
	global_store_dwordx4 v160, v[132:135], s[100:101] offset:64 sc1
	s_add_u32 s100, s100, 0x8000
	s_addc_u32 s101, s101, 0
	v_cvt_pk_bf16_f32 v124, v124, v125
	v_cvt_pk_bf16_f32 v125, v126, v127
	v_cvt_pk_bf16_f32 v126, v120, v121
	v_cvt_pk_bf16_f32 v127, v122, v123
	v_cvt_pk_bf16_f32 v116, v116, v117
	v_cvt_pk_bf16_f32 v117, v118, v119
	v_cvt_pk_bf16_f32 v118, v112, v113
	v_cvt_pk_bf16_f32 v119, v114, v115
	v_permlane16_swap_b32_e32 v124, v126
	v_permlane16_swap_b32_e32 v125, v127
	v_permlane16_swap_b32_e32 v116, v118
	v_permlane16_swap_b32_e32 v117, v119
	global_store_dwordx4 v160, v[124:127], s[100:101] sc1
	global_store_dwordx4 v160, v[116:119], s[100:101] offset:64 sc1
	s_add_u32 s100, s100, 0x8000
	s_addc_u32 s101, s101, 0
	v_cvt_pk_bf16_f32 v108, v108, v109
	v_cvt_pk_bf16_f32 v109, v110, v111
	v_cvt_pk_bf16_f32 v110, v104, v105
	v_cvt_pk_bf16_f32 v111, v106, v107
	v_cvt_pk_bf16_f32 v100, v100, v101
	v_cvt_pk_bf16_f32 v101, v102, v103
	v_cvt_pk_bf16_f32 v102, v96, v97
	v_cvt_pk_bf16_f32 v103, v98, v99
	v_permlane16_swap_b32_e32 v108, v110
	v_permlane16_swap_b32_e32 v109, v111
	v_permlane16_swap_b32_e32 v100, v102
	v_permlane16_swap_b32_e32 v101, v103
	global_store_dwordx4 v160, v[108:111], s[100:101] sc1
	global_store_dwordx4 v160, v[100:103], s[100:101] offset:64 sc1
	s_add_u32 s100, s100, 0x8000
	s_addc_u32 s101, s101, 0
	v_cvt_pk_bf16_f32 v92, v92, v93
	v_cvt_pk_bf16_f32 v93, v94, v95
	v_cvt_pk_bf16_f32 v94, v88, v89
	v_cvt_pk_bf16_f32 v95, v90, v91
	v_cvt_pk_bf16_f32 v80, v80, v81
	v_cvt_pk_bf16_f32 v81, v82, v83
	v_cvt_pk_bf16_f32 v82, v84, v85
	v_cvt_pk_bf16_f32 v83, v86, v87
	v_permlane16_swap_b32_e32 v92, v94
	v_permlane16_swap_b32_e32 v93, v95
	v_permlane16_swap_b32_e32 v80, v82
	v_permlane16_swap_b32_e32 v81, v83
	global_store_dwordx4 v160, v[92:95], s[100:101] sc1
	global_store_dwordx4 v160, v[80:83], s[100:101] offset:64 sc1
	s_add_u32 s100, s100, 0x8000
	s_addc_u32 s101, s101, 0
	v_cvt_pk_bf16_f32 v76, v76, v77
	v_cvt_pk_bf16_f32 v77, v78, v79
	v_cvt_pk_bf16_f32 v78, v72, v73
	v_cvt_pk_bf16_f32 v79, v74, v75
	v_cvt_pk_bf16_f32 v68, v68, v69
	v_cvt_pk_bf16_f32 v69, v70, v71
	v_cvt_pk_bf16_f32 v70, v64, v65
	v_cvt_pk_bf16_f32 v71, v66, v67
	v_permlane16_swap_b32_e32 v76, v78
	v_permlane16_swap_b32_e32 v77, v79
	v_permlane16_swap_b32_e32 v68, v70
	v_permlane16_swap_b32_e32 v69, v71
	global_store_dwordx4 v160, v[76:79], s[100:101] sc1
	global_store_dwordx4 v160, v[68:71], s[100:101] offset:64 sc1
	s_add_u32 s100, s100, 0x8000
	s_addc_u32 s101, s101, 0
	v_cvt_pk_bf16_f32 v60, v60, v61
	v_cvt_pk_bf16_f32 v61, v62, v63
	v_cvt_pk_bf16_f32 v62, v56, v57
	v_cvt_pk_bf16_f32 v63, v58, v59
	v_cvt_pk_bf16_f32 v52, v52, v53
	v_cvt_pk_bf16_f32 v53, v54, v55
	v_cvt_pk_bf16_f32 v54, v48, v49
	v_cvt_pk_bf16_f32 v55, v50, v51
	v_permlane16_swap_b32_e32 v60, v62
	v_permlane16_swap_b32_e32 v61, v63
	v_permlane16_swap_b32_e32 v52, v54
	v_permlane16_swap_b32_e32 v53, v55
	global_store_dwordx4 v160, v[60:63], s[100:101] sc1
	global_store_dwordx4 v160, v[52:55], s[100:101] offset:64 sc1
	s_add_u32 s100, s100, 0x8000
	s_addc_u32 s101, s101, 0
	v_cvt_pk_bf16_f32 v40, v40, v41
	v_cvt_pk_bf16_f32 v41, v42, v43
	v_cvt_pk_bf16_f32 v42, v36, v37
	v_cvt_pk_bf16_f32 v43, v38, v39
	v_cvt_pk_bf16_f32 v32, v32, v33
	v_cvt_pk_bf16_f32 v33, v34, v35
	v_cvt_pk_bf16_f32 v34, v44, v45
	v_cvt_pk_bf16_f32 v35, v46, v47
	v_permlane16_swap_b32_e32 v40, v42
	v_permlane16_swap_b32_e32 v41, v43
	v_permlane16_swap_b32_e32 v32, v34
	v_permlane16_swap_b32_e32 v33, v35
	global_store_dwordx4 v160, v[40:43], s[100:101] sc1
	global_store_dwordx4 v160, v[32:35], s[100:101] offset:64 sc1
	s_and_b64 vcc, exec, s[54:55]
	s_mov_b32 s78, s77
	s_mov_b32 s79, s76
	s_mov_b32 s80, s75
	s_mov_b64 s[58:59], s[52:53]
	s_mov_b64 s[56:57], s[50:51]
	s_cbranch_vccz .LBB0_1508
	s_load_dwordx4 s[84:87], s[0:1], 0x100
	s_mov_b64 s[92:93], s[96:97]
